# L1/L2 out-projection: accumulators start at x_old (16 loads before the K-loop) - epilogue no longer does a 16-deep load/add/store chain
# baseline (speedup 1.0000x reference)
; __device__ __forceinline__ float bflo(unsigned u) { return __uint_as_float(u << 16); }
; __device__ __forceinline__ float bfhi(unsigned u) { return __uint_as_float(u & 0xffff0000u); }
; template <class Epi, class Sched, bool ALIGN_EPI = false, bool SP2 = false>
; __device__ __forceinline__ void gemm_phase(PG8_LAS unsigned char* lds, const Gemm g, const Sched& S, const Epi& E) {
;     ...
; #pragma unroll
;     for (int a = 0; a < 2; ++a)
; #pragma unroll
;         for (int b = 0; b < 2; ++b)
; #pragma unroll
;             for (int m = 0; m < 4; ++m)
; #pragma unroll
;                 for (int n = 0; n < 2; ++n) acc[a][b][m][n] = (f32x4){0.f, 0.f, 0.f, 0.f};
;     bf16x8 At[4][2], B0[2][2], B1[2][2];
;     const char* cA = (const char*)g.A + (size_t)cur.pm * tstep; const char* cB = (const char*)g.Bt + (size_t)cur.pn * tstep;
;     __device__ __forceinline__ void operator()(const f32x4 (&acc)[2][2][4][2], const pg8::Unit& u, int wr, int wc, int fr, int fq) const {
;     ...
;                     const size_t off = (size_t)row * 1024 + c0 + bj * 128;
;                     f32x4 x0, x1;
;                     if (xin) { x0 = *(const f32x4*)(xin + off); x1 = *(const f32x4*)(xin + off + 4); }
;                     else { const v4u xv = *(const v4u*)(xb + off); x0 = (f32x4){bflo(xv.x), bfhi(xv.x), bflo(xv.y), bfhi(xv.y)}; x1 = (f32x4){bflo(xv.z), bfhi(xv.z), bflo(xv.w), bfhi(xv.w)}; }
.LBB0_463:
	s_ashr_i32 s13, s12, 31
	s_lshl_b64 s[14:15], s[12:13], 19
	s_add_u32 s14, s50, s14
	s_addc_u32 s15, s51, s15
	s_and_b64 s[18:19], s[4:5], exec
	s_cselect_b32 s13, s15, s3
	s_cselect_b32 s39, s14, s2
	s_ashr_i32 s11, s10, 31
	s_lshl_b64 s[18:19], s[10:11], 19
	v_readlane_b32 s22, v254, 3
	v_readlane_b32 s23, v254, 4
	s_add_u32 s18, s22, s18
	s_addc_u32 s19, s23, s19
	s_and_b64 s[22:23], s[4:5], exec
	s_cselect_b32 s11, s19, s21
	s_cselect_b32 s42, s18, s20
	s_add_u32 s2, s2, 0x40080
	s_addc_u32 s3, s3, 0
	s_add_u32 s43, s20, 0x100
	v_mov_b32_e32 v2, 0
	s_addc_u32 s44, s21, 0
	s_mov_b32 s45, -2
	s_waitcnt lgkmcnt(0)
	v_mov_b32_e32 v3, v2
	v_mov_b32_e32 v4, v2
	v_mov_b32_e32 v5, v2
	v_mov_b32_e32 v6, v2
	v_mov_b32_e32 v7, v2
	v_mov_b32_e32 v8, v2
	v_mov_b32_e32 v9, v2
	v_mov_b32_e32 v18, v2
	v_mov_b32_e32 v19, v2
	v_mov_b32_e32 v20, v2
	v_mov_b32_e32 v21, v2
	v_mov_b32_e32 v22, v2
	v_mov_b32_e32 v23, v2
	v_mov_b32_e32 v24, v2
	v_mov_b32_e32 v25, v2
	v_mov_b32_e32 v34, v2
	v_mov_b32_e32 v35, v2
	v_mov_b32_e32 v36, v2
	v_mov_b32_e32 v37, v2
	v_mov_b32_e32 v38, v2
	v_mov_b32_e32 v39, v2
	v_mov_b32_e32 v40, v2
	v_mov_b32_e32 v41, v2
	s_waitcnt vmcnt(0)
	v_mov_b32_e32 v50, v2
	v_mov_b32_e32 v51, v2
	v_mov_b32_e32 v52, v2
	v_mov_b32_e32 v53, v2
	v_mov_b32_e32 v54, v2
	v_mov_b32_e32 v55, v2
	v_mov_b32_e32 v56, v2
	v_mov_b32_e32 v57, v2
	v_mov_b32_e32 v10, v2
	v_mov_b32_e32 v11, v2
	v_mov_b32_e32 v12, v2
	v_mov_b32_e32 v13, v2
	v_mov_b32_e32 v14, v2
	v_mov_b32_e32 v15, v2
	v_mov_b32_e32 v16, v2
	v_mov_b32_e32 v17, v2
	v_mov_b32_e32 v26, v2
	v_mov_b32_e32 v27, v2
	v_mov_b32_e32 v28, v2
	v_mov_b32_e32 v29, v2
	v_mov_b32_e32 v30, v2
	v_mov_b32_e32 v31, v2
	v_mov_b32_e32 v32, v2
	v_mov_b32_e32 v33, v2
	v_mov_b32_e32 v42, v2
	v_mov_b32_e32 v43, v2
	v_mov_b32_e32 v44, v2
	v_mov_b32_e32 v45, v2
	v_mov_b32_e32 v46, v2
	v_mov_b32_e32 v47, v2
	v_mov_b32_e32 v48, v2
	v_mov_b32_e32 v49, v2
	v_mov_b32_e32 v58, v2
	v_mov_b32_e32 v59, v2
	v_mov_b32_e32 v60, v2
	v_mov_b32_e32 v61, v2
	v_mov_b32_e32 v62, v2
	v_mov_b32_e32 v63, v2
	v_mov_b32_e32 v64, v2
	v_mov_b32_e32 v65, v2
	v_mov_b32_e32 v66, v2
	v_mov_b32_e32 v67, v2
	v_mov_b32_e32 v68, v2
	v_mov_b32_e32 v69, v2
	v_mov_b32_e32 v70, v2
	v_mov_b32_e32 v71, v2
	v_mov_b32_e32 v72, v2
	v_mov_b32_e32 v73, v2
	v_mov_b32_e32 v82, v2
	v_mov_b32_e32 v83, v2
	v_mov_b32_e32 v84, v2
	v_mov_b32_e32 v85, v2
	v_mov_b32_e32 v86, v2
	v_mov_b32_e32 v87, v2
	v_mov_b32_e32 v88, v2
	v_mov_b32_e32 v89, v2
	v_mov_b32_e32 v98, v2
	v_mov_b32_e32 v99, v2
	v_mov_b32_e32 v100, v2
	v_mov_b32_e32 v101, v2
	v_mov_b32_e32 v102, v2
	v_mov_b32_e32 v103, v2
	v_mov_b32_e32 v104, v2
	v_mov_b32_e32 v105, v2
	v_mov_b32_e32 v114, v2
	v_mov_b32_e32 v115, v2
	v_mov_b32_e32 v116, v2
	v_mov_b32_e32 v117, v2
	v_mov_b32_e32 v118, v2
	v_mov_b32_e32 v119, v2
	v_mov_b32_e32 v120, v2
	v_mov_b32_e32 v121, v2
	v_mov_b32_e32 v74, v2
	v_mov_b32_e32 v75, v2
	v_mov_b32_e32 v76, v2
	v_mov_b32_e32 v77, v2
	v_mov_b32_e32 v78, v2
	v_mov_b32_e32 v79, v2
	v_mov_b32_e32 v80, v2
	v_mov_b32_e32 v81, v2
	v_mov_b32_e32 v90, v2
	v_mov_b32_e32 v91, v2
	v_mov_b32_e32 v92, v2
	v_mov_b32_e32 v93, v2
	v_mov_b32_e32 v94, v2
	v_mov_b32_e32 v95, v2
	v_mov_b32_e32 v96, v2
	v_mov_b32_e32 v97, v2
	v_mov_b32_e32 v106, v2
	v_mov_b32_e32 v107, v2
	v_mov_b32_e32 v108, v2
	v_mov_b32_e32 v109, v2
	v_mov_b32_e32 v110, v2
	v_mov_b32_e32 v111, v2
	v_mov_b32_e32 v112, v2
	v_mov_b32_e32 v113, v2
	v_mov_b32_e32 v122, v2
	v_mov_b32_e32 v123, v2
	v_mov_b32_e32 v124, v2
	v_mov_b32_e32 v125, v2
	v_mov_b32_e32 v126, v2
	v_mov_b32_e32 v127, v2
	v_mov_b32_e32 v128, v2
	v_mov_b32_e32 v129, v2
	v_readlane_b32 s100, v255, 22
	v_readlane_b32 s101, v255, 23
	v_lshl_add_u32 v196, s38, 8, v1
	v_lshl_or_b32 v198, s37, 8, v170
	v_ashrrev_i32_e32 v197, 31, v196
	v_ashrrev_i32_e32 v199, 31, v198
	v_lshlrev_b64 v[200:201], 10, v[196:197]
	v_lshl_add_u64 v[200:201], v[200:201], 0, v[198:199]
	v_lshl_add_u64 v[200:201], v[200:201], 1, s[100:101]
	v_mov_b32_e32 v217, 0
	v_mov_b32_e32 v216, 0x8000
	v_lshl_add_u64 v[202:203], v[200:201], 0, v[216:217]
	v_mov_b32_e32 v216, 0x10000
	v_lshl_add_u64 v[204:205], v[200:201], 0, v[216:217]
	v_mov_b32_e32 v216, 0x18000
	v_lshl_add_u64 v[206:207], v[200:201], 0, v[216:217]
	v_mov_b32_e32 v216, 0x40000
	v_lshl_add_u64 v[208:209], v[200:201], 0, v[216:217]
	v_mov_b32_e32 v216, 0x48000
	v_lshl_add_u64 v[210:211], v[200:201], 0, v[216:217]
	v_mov_b32_e32 v216, 0x50000
	v_lshl_add_u64 v[212:213], v[200:201], 0, v[216:217]
	v_mov_b32_e32 v216, 0x58000
	v_lshl_add_u64 v[214:215], v[200:201], 0, v[216:217]
	global_load_dwordx4 v[122:125], v[200:201], off
	global_load_dwordx4 v[114:117], v[200:201], off offset:256
	global_load_dwordx4 v[106:109], v[202:203], off
	global_load_dwordx4 v[98:101], v[202:203], off offset:256
	global_load_dwordx4 v[90:93], v[204:205], off
	global_load_dwordx4 v[82:85], v[204:205], off offset:256
	global_load_dwordx4 v[74:77], v[206:207], off
	global_load_dwordx4 v[66:69], v[206:207], off offset:256
	global_load_dwordx4 v[58:61], v[208:209], off
	global_load_dwordx4 v[50:53], v[208:209], off offset:256
	global_load_dwordx4 v[42:45], v[210:211], off
	global_load_dwordx4 v[34:37], v[210:211], off offset:256
	global_load_dwordx4 v[26:29], v[212:213], off
	global_load_dwordx4 v[18:21], v[212:213], off offset:256
	global_load_dwordx4 v[10:13], v[214:215], off
	global_load_dwordx4 v[2:5], v[214:215], off offset:256
	s_waitcnt vmcnt(0)
; __device__ __forceinline__ float bflo(unsigned u) { return __uint_as_float(u << 16); }
; __device__ __forceinline__ float bfhi(unsigned u) { return __uint_as_float(u & 0xffff0000u); }
;     __device__ __forceinline__ void operator()(const f32x4 (&acc)[2][2][4][2], const pg8::Unit& u, int wr, int wc, int fr, int fq) const {
;     ...
;                     else { const v4u xv = *(const v4u*)(xb + off); x0 = (f32x4){bflo(xv.x), bfhi(xv.x), bflo(xv.y), bfhi(xv.y)}; x1 = (f32x4){bflo(xv.z), bfhi(xv.z), bflo(xv.w), bfhi(xv.w)}; }
;                     const f32x4 n0 = x0 + acc[ai][bj][m][0], n1 = x1 + acc[ai][bj][m][1];
	v_lshlrev_b32_e32 v126, 16, v122
	v_and_b32_e32 v127, 0xffff0000, v122
	v_lshlrev_b32_e32 v128, 16, v123
	v_and_b32_e32 v129, 0xffff0000, v123
	v_lshlrev_b32_e32 v122, 16, v124
	v_and_b32_e32 v123, 0xffff0000, v124
	v_lshlrev_b32_e32 v124, 16, v125
	v_and_b32_e32 v125, 0xffff0000, v125
	v_lshlrev_b32_e32 v118, 16, v114
	v_and_b32_e32 v119, 0xffff0000, v114
	v_lshlrev_b32_e32 v120, 16, v115
	v_and_b32_e32 v121, 0xffff0000, v115
	v_lshlrev_b32_e32 v114, 16, v116
	v_and_b32_e32 v115, 0xffff0000, v116
	v_lshlrev_b32_e32 v116, 16, v117
	v_and_b32_e32 v117, 0xffff0000, v117
	v_lshlrev_b32_e32 v110, 16, v106
	v_and_b32_e32 v111, 0xffff0000, v106
	v_lshlrev_b32_e32 v112, 16, v107
	v_and_b32_e32 v113, 0xffff0000, v107
	v_lshlrev_b32_e32 v106, 16, v108
	v_and_b32_e32 v107, 0xffff0000, v108
	v_lshlrev_b32_e32 v108, 16, v109
	v_and_b32_e32 v109, 0xffff0000, v109
	v_lshlrev_b32_e32 v102, 16, v98
	v_and_b32_e32 v103, 0xffff0000, v98
	v_lshlrev_b32_e32 v104, 16, v99
	v_and_b32_e32 v105, 0xffff0000, v99
	v_lshlrev_b32_e32 v98, 16, v100
	v_and_b32_e32 v99, 0xffff0000, v100
	v_lshlrev_b32_e32 v100, 16, v101
	v_and_b32_e32 v101, 0xffff0000, v101
	v_lshlrev_b32_e32 v94, 16, v90
	v_and_b32_e32 v95, 0xffff0000, v90
	v_lshlrev_b32_e32 v96, 16, v91
	v_and_b32_e32 v97, 0xffff0000, v91
	v_lshlrev_b32_e32 v90, 16, v92
	v_and_b32_e32 v91, 0xffff0000, v92
	v_lshlrev_b32_e32 v92, 16, v93
	v_and_b32_e32 v93, 0xffff0000, v93
	v_lshlrev_b32_e32 v86, 16, v82
	v_and_b32_e32 v87, 0xffff0000, v82
	v_lshlrev_b32_e32 v88, 16, v83
	v_and_b32_e32 v89, 0xffff0000, v83
	v_lshlrev_b32_e32 v82, 16, v84
	v_and_b32_e32 v83, 0xffff0000, v84
	v_lshlrev_b32_e32 v84, 16, v85
	v_and_b32_e32 v85, 0xffff0000, v85
	v_lshlrev_b32_e32 v78, 16, v74
	v_and_b32_e32 v79, 0xffff0000, v74
	v_lshlrev_b32_e32 v80, 16, v75
	v_and_b32_e32 v81, 0xffff0000, v75
	v_lshlrev_b32_e32 v74, 16, v76
	v_and_b32_e32 v75, 0xffff0000, v76
	v_lshlrev_b32_e32 v76, 16, v77
	v_and_b32_e32 v77, 0xffff0000, v77
	v_lshlrev_b32_e32 v70, 16, v66
	v_and_b32_e32 v71, 0xffff0000, v66
	v_lshlrev_b32_e32 v72, 16, v67
	v_and_b32_e32 v73, 0xffff0000, v67
	v_lshlrev_b32_e32 v66, 16, v68
	v_and_b32_e32 v67, 0xffff0000, v68
	v_lshlrev_b32_e32 v68, 16, v69
	v_and_b32_e32 v69, 0xffff0000, v69
	v_lshlrev_b32_e32 v62, 16, v58
	v_and_b32_e32 v63, 0xffff0000, v58
	v_lshlrev_b32_e32 v64, 16, v59
	v_and_b32_e32 v65, 0xffff0000, v59
	v_lshlrev_b32_e32 v58, 16, v60
	v_and_b32_e32 v59, 0xffff0000, v60
	v_lshlrev_b32_e32 v60, 16, v61
	v_and_b32_e32 v61, 0xffff0000, v61
	v_lshlrev_b32_e32 v54, 16, v50
	v_and_b32_e32 v55, 0xffff0000, v50
	v_lshlrev_b32_e32 v56, 16, v51
	v_and_b32_e32 v57, 0xffff0000, v51
	v_lshlrev_b32_e32 v50, 16, v52
	v_and_b32_e32 v51, 0xffff0000, v52
	v_lshlrev_b32_e32 v52, 16, v53
	v_and_b32_e32 v53, 0xffff0000, v53
	v_lshlrev_b32_e32 v46, 16, v42
	v_and_b32_e32 v47, 0xffff0000, v42
	v_lshlrev_b32_e32 v48, 16, v43
	v_and_b32_e32 v49, 0xffff0000, v43
	v_lshlrev_b32_e32 v42, 16, v44
	v_and_b32_e32 v43, 0xffff0000, v44
	v_lshlrev_b32_e32 v44, 16, v45
	v_and_b32_e32 v45, 0xffff0000, v45
	v_lshlrev_b32_e32 v38, 16, v34
	v_and_b32_e32 v39, 0xffff0000, v34
	v_lshlrev_b32_e32 v40, 16, v35
	v_and_b32_e32 v41, 0xffff0000, v35
	v_lshlrev_b32_e32 v34, 16, v36
	v_and_b32_e32 v35, 0xffff0000, v36
	v_lshlrev_b32_e32 v36, 16, v37
	v_and_b32_e32 v37, 0xffff0000, v37
	v_lshlrev_b32_e32 v30, 16, v26
	v_and_b32_e32 v31, 0xffff0000, v26
	v_lshlrev_b32_e32 v32, 16, v27
	v_and_b32_e32 v33, 0xffff0000, v27
	v_lshlrev_b32_e32 v26, 16, v28
	v_and_b32_e32 v27, 0xffff0000, v28
	v_lshlrev_b32_e32 v28, 16, v29
	v_and_b32_e32 v29, 0xffff0000, v29
	v_lshlrev_b32_e32 v22, 16, v18
	v_and_b32_e32 v23, 0xffff0000, v18
	v_lshlrev_b32_e32 v24, 16, v19
	v_and_b32_e32 v25, 0xffff0000, v19
	v_lshlrev_b32_e32 v18, 16, v20
	v_and_b32_e32 v19, 0xffff0000, v20
	v_lshlrev_b32_e32 v20, 16, v21
	v_and_b32_e32 v21, 0xffff0000, v21
	v_lshlrev_b32_e32 v14, 16, v10
	v_and_b32_e32 v15, 0xffff0000, v10
	v_lshlrev_b32_e32 v16, 16, v11
	v_and_b32_e32 v17, 0xffff0000, v11
	v_lshlrev_b32_e32 v10, 16, v12
	v_and_b32_e32 v11, 0xffff0000, v12
	v_lshlrev_b32_e32 v12, 16, v13
	v_and_b32_e32 v13, 0xffff0000, v13
	v_lshlrev_b32_e32 v6, 16, v2
	v_and_b32_e32 v7, 0xffff0000, v2
	v_lshlrev_b32_e32 v8, 16, v3
	v_and_b32_e32 v9, 0xffff0000, v3
	v_lshlrev_b32_e32 v2, 16, v4
	v_and_b32_e32 v3, 0xffff0000, v4
	v_lshlrev_b32_e32 v4, 16, v5
	v_and_b32_e32 v5, 0xffff0000, v5

; __device__ __forceinline__ float bflo(unsigned u) { return __uint_as_float(u << 16); }
; __device__ __forceinline__ float bfhi(unsigned u) { return __uint_as_float(u & 0xffff0000u); }
; __device__ __forceinline__ unsigned pk2(float lo, float hi) { f32x2_t v = {lo, hi}; bf16x2_t b = __builtin_convertvector(v, bf16x2_t); return __builtin_bit_cast(unsigned, b); }
; __device__ __forceinline__ void atomic_add_agent(float* p, float v) { (void)__hip_atomic_fetch_add(p, v, __ATOMIC_RELAXED, __HIP_MEMORY_SCOPE_AGENT); }
;     __device__ __forceinline__ void operator()(const f32x4 (&acc)[2][2][4][2], const pg8::Unit& u, int wr, int wc, int fr, int fq) const {
;         const int row0 = u.pm * 256 + wr * 64 + fr; const int c0 = u.pn * 256 + wc * 32 + 8 * fq;
; #pragma unroll
;         for (int ai = 0; ai < 2; ++ai)
; #pragma unroll
;             for (int m = 0; m < 4; ++m) {
;                 const int row = row0 + ai * 128 + m * 16; float s2 = 0.f;
; #pragma unroll
;                 for (int bj = 0; bj < 2; ++bj) {
;                     const size_t off = (size_t)row * 1024 + c0 + bj * 128;
;                     f32x4 x0, x1;
;                     if (xin) { x0 = *(const f32x4*)(xin + off); x1 = *(const f32x4*)(xin + off + 4); }
;                     else { const v4u xv = *(const v4u*)(xb + off); x0 = (f32x4){bflo(xv.x), bfhi(xv.x), bflo(xv.y), bfhi(xv.y)}; x1 = (f32x4){bflo(xv.z), bfhi(xv.z), bflo(xv.w), bfhi(xv.w)}; }
;                     const f32x4 n0 = x0 + acc[ai][bj][m][0], n1 = x1 + acc[ai][bj][m][1];
;                     if (xout) { *(f32x4*)(xout + off) = n0; *(f32x4*)(xout + off + 4) = n1; }
;                     else *(v4u*)(xb + off) = (v4u){pk2(n0[0], n0[1]), pk2(n0[2], n0[3]), pk2(n1[0], n1[1]), pk2(n1[2], n1[3])};
;                     s2 += ((n0[0] * n0[0] + n0[1] * n0[1]) + (n0[2] * n0[2] + n0[3] * n0[3])) + ((n1[0] * n1[0] + n1[1] * n1[1]) + (n1[2] * n1[2] + n1[3] * n1[3]));
;                 }
;                 if (ssq) { s2 += __shfl_xor(s2, 16); s2 += __shfl_xor(s2, 32); if (fq == 0) atomic_add_agent(ssq + row, s2); }
.LBB0_467:
	v_lshl_add_u32 v168, s38, 8, v1
	v_lshl_or_b32 v166, s37, 8, v170
	v_ashrrev_i32_e32 v169, 31, v168
	v_ashrrev_i32_e32 v167, 31, v166
	v_lshlrev_b64 v[150:151], 10, v[168:169]
	v_readlane_b32 s2, v255, 22
	v_lshl_add_u64 v[150:151], v[150:151], 0, v[166:167]
	v_readlane_b32 s3, v255, 23
	s_nop 1
	v_lshl_add_u64 v[150:151], v[150:151], 1, s[2:3]
	v_mov_b32_e32 v152, v124
	v_mov_b32_e32 v153, v125
	v_mov_b32_e32 v154, v122
	v_mov_b32_e32 v155, v123
	v_cvt_pk_bf16_f32 v122, v126, v127
	v_cvt_pk_bf16_f32 v123, v128, v129
	v_cvt_pk_bf16_f32 v124, v154, v155
	v_cvt_pk_bf16_f32 v125, v152, v153
	global_store_dwordx4 v[150:151], v[122:125], off
	s_nop 1
	v_mul_f32_e32 v122, v127, v127
	v_mul_f32_e32 v123, v129, v129
	v_fmac_f32_e32 v122, v126, v126
	v_fmac_f32_e32 v123, v128, v128
	v_add_f32_e32 v122, v122, v123
	v_mul_f32_e32 v123, v155, v155
	v_mul_f32_e32 v124, v153, v153
	v_fmac_f32_e32 v123, v154, v154
	v_fmac_f32_e32 v124, v152, v152
	v_add_f32_e32 v123, v123, v124
	v_add_f32_e32 v152, v122, v123
	v_mov_b32_e32 v122, v116
	v_mov_b32_e32 v123, v117
	v_mov_b32_e32 v124, v114
	v_mov_b32_e32 v125, v115
	v_cvt_pk_bf16_f32 v114, v118, v119
	v_cvt_pk_bf16_f32 v115, v120, v121
	v_cvt_pk_bf16_f32 v116, v124, v125
	v_cvt_pk_bf16_f32 v117, v122, v123
	global_store_dwordx4 v[150:151], v[114:117], off offset:256
	s_nop 1
	v_mul_f32_e32 v114, v119, v119
	v_mul_f32_e32 v115, v121, v121
	v_fmac_f32_e32 v114, v118, v118
	v_fmac_f32_e32 v115, v120, v120
	v_add_f32_e32 v114, v114, v115
	v_mul_f32_e32 v115, v125, v125
	v_mul_f32_e32 v116, v123, v123
	v_fmac_f32_e32 v115, v124, v124
	v_fmac_f32_e32 v116, v122, v122
	v_add_f32_e32 v115, v115, v116
	v_and_b32_e32 v116, 64, v191
	v_add_f32_e32 v114, v114, v115
	v_xor_b32_e32 v115, 16, v191
	v_add_u32_e32 v117, 64, v116
	v_cmp_lt_i32_e32 vcc, v115, v117
	v_add_f32_e32 v114, v152, v114
	s_nop 0
	v_cndmask_b32_e32 v115, v191, v115, vcc
	v_lshlrev_b32_e32 v116, 2, v115
	ds_bpermute_b32 v115, v116, v114
	s_waitcnt lgkmcnt(0)
	v_add_f32_e32 v114, v114, v115
	v_xor_b32_e32 v115, 32, v191
	v_cmp_lt_i32_e32 vcc, v115, v117
	s_nop 1
	v_cndmask_b32_e32 v115, v191, v115, vcc
	v_lshlrev_b32_e32 v117, 2, v115
	ds_bpermute_b32 v115, v117, v114
	s_and_saveexec_b64 s[2:3], s[0:1]
	s_cbranch_execz .LBB0_469
	v_readlane_b32 s20, v252, 60
	v_readlane_b32 s21, v252, 61
	s_waitcnt lgkmcnt(0)
	v_add_f32_e32 v114, v114, v115
	v_lshl_add_u64 v[118:119], v[168:169], 2, s[20:21]
	global_atomic_add_f32 v[118:119], v114, off
.LBB0_469:
	s_or_b64 exec, exec, s[2:3]
	v_or_b32_e32 v114, 16, v168
	s_waitcnt lgkmcnt(0)
	v_ashrrev_i32_e32 v115, 31, v114
	v_lshlrev_b64 v[118:119], 10, v[114:115]
	v_readlane_b32 s2, v255, 22
	v_lshl_add_u64 v[118:119], v[118:119], 0, v[166:167]
	v_readlane_b32 s3, v255, 23
	s_nop 1
	v_lshl_add_u64 v[122:123], v[118:119], 1, s[2:3]
	v_mov_b32_e32 v118, v108
	v_mov_b32_e32 v119, v109
	v_mov_b32_e32 v120, v106
	v_mov_b32_e32 v121, v107
	v_cvt_pk_bf16_f32 v106, v110, v111
	v_cvt_pk_bf16_f32 v107, v112, v113
	v_cvt_pk_bf16_f32 v108, v120, v121
	v_cvt_pk_bf16_f32 v109, v118, v119
	global_store_dwordx4 v[122:123], v[106:109], off
	s_nop 1
	v_mul_f32_e32 v106, v111, v111
	v_mul_f32_e32 v107, v113, v113
	v_fmac_f32_e32 v106, v110, v110
	v_fmac_f32_e32 v107, v112, v112
	v_add_f32_e32 v106, v106, v107
	v_mul_f32_e32 v107, v121, v121
	v_mul_f32_e32 v108, v119, v119
	v_fmac_f32_e32 v107, v120, v120
	v_fmac_f32_e32 v108, v118, v118
	v_add_f32_e32 v107, v107, v108
	v_add_f32_e32 v118, v106, v107
	v_mov_b32_e32 v106, v100
	v_mov_b32_e32 v107, v101
	v_mov_b32_e32 v108, v98
	v_mov_b32_e32 v109, v99
	v_cvt_pk_bf16_f32 v98, v102, v103
	v_cvt_pk_bf16_f32 v99, v104, v105
	v_cvt_pk_bf16_f32 v100, v108, v109
	v_cvt_pk_bf16_f32 v101, v106, v107
	global_store_dwordx4 v[122:123], v[98:101], off offset:256
	s_nop 1
	v_mul_f32_e32 v98, v103, v103
	v_mul_f32_e32 v99, v105, v105
	v_fmac_f32_e32 v98, v102, v102
	v_fmac_f32_e32 v99, v104, v104
	v_add_f32_e32 v98, v98, v99
	v_mul_f32_e32 v99, v109, v109
	v_mul_f32_e32 v100, v107, v107
	v_fmac_f32_e32 v99, v108, v108
	v_fmac_f32_e32 v100, v106, v106
	v_add_f32_e32 v99, v99, v100
	v_add_f32_e32 v98, v98, v99
	v_add_f32_e32 v98, v118, v98
	ds_bpermute_b32 v99, v116, v98
	s_waitcnt lgkmcnt(0)
	v_add_f32_e32 v98, v98, v99
	ds_bpermute_b32 v99, v117, v98
	s_and_saveexec_b64 s[2:3], s[0:1]
	s_cbranch_execz .LBB0_471
	v_readlane_b32 s20, v252, 60
	v_readlane_b32 s21, v252, 61
	s_waitcnt lgkmcnt(0)
	v_add_f32_e32 v98, v98, v99
	v_lshl_add_u64 v[100:101], v[114:115], 2, s[20:21]
	global_atomic_add_f32 v[100:101], v98, off
.LBB0_471:
	s_or_b64 exec, exec, s[2:3]
	v_or_b32_e32 v98, 32, v168
	s_waitcnt lgkmcnt(0)
	v_ashrrev_i32_e32 v99, 31, v98
	v_lshlrev_b64 v[100:101], 10, v[98:99]
	v_readlane_b32 s2, v255, 22
	v_lshl_add_u64 v[100:101], v[100:101], 0, v[166:167]
	v_readlane_b32 s3, v255, 23
	s_nop 1
	v_lshl_add_u64 v[104:105], v[100:101], 1, s[2:3]
	v_mov_b32_e32 v100, v92
	v_mov_b32_e32 v101, v93
	v_mov_b32_e32 v102, v90
	v_mov_b32_e32 v103, v91
	v_cvt_pk_bf16_f32 v90, v94, v95
	v_cvt_pk_bf16_f32 v91, v96, v97
	v_cvt_pk_bf16_f32 v92, v102, v103
	v_cvt_pk_bf16_f32 v93, v100, v101
	global_store_dwordx4 v[104:105], v[90:93], off
	s_nop 1
	v_mul_f32_e32 v90, v95, v95
	v_mul_f32_e32 v91, v97, v97
	v_fmac_f32_e32 v90, v94, v94
	v_fmac_f32_e32 v91, v96, v96
	v_add_f32_e32 v90, v90, v91
	v_mul_f32_e32 v91, v103, v103
	v_mul_f32_e32 v92, v101, v101
	v_fmac_f32_e32 v91, v102, v102
	v_fmac_f32_e32 v92, v100, v100
	v_add_f32_e32 v91, v91, v92
	v_add_f32_e32 v100, v90, v91
	v_mov_b32_e32 v90, v84
	v_mov_b32_e32 v91, v85
	v_mov_b32_e32 v92, v82
	v_mov_b32_e32 v93, v83
	v_cvt_pk_bf16_f32 v82, v86, v87
	v_cvt_pk_bf16_f32 v83, v88, v89
	v_cvt_pk_bf16_f32 v84, v92, v93
	v_cvt_pk_bf16_f32 v85, v90, v91
	global_store_dwordx4 v[104:105], v[82:85], off offset:256
	s_nop 1
	v_mul_f32_e32 v82, v87, v87
	v_mul_f32_e32 v83, v89, v89
	v_fmac_f32_e32 v82, v86, v86
	v_fmac_f32_e32 v83, v88, v88
	v_add_f32_e32 v82, v82, v83
	v_mul_f32_e32 v83, v93, v93
	v_mul_f32_e32 v84, v91, v91
	v_fmac_f32_e32 v83, v92, v92
	v_fmac_f32_e32 v84, v90, v90
	v_add_f32_e32 v83, v83, v84
	v_add_f32_e32 v82, v82, v83
	v_add_f32_e32 v82, v100, v82
	ds_bpermute_b32 v83, v116, v82
	s_waitcnt lgkmcnt(0)
	v_add_f32_e32 v82, v82, v83
	ds_bpermute_b32 v83, v117, v82
	s_and_saveexec_b64 s[2:3], s[0:1]
	s_cbranch_execz .LBB0_473
	v_readlane_b32 s20, v252, 60
	v_readlane_b32 s21, v252, 61
	s_waitcnt lgkmcnt(0)
	v_add_f32_e32 v82, v82, v83
	v_lshl_add_u64 v[84:85], v[98:99], 2, s[20:21]
	global_atomic_add_f32 v[84:85], v82, off
; __device__ __forceinline__ float bflo(unsigned u) { return __uint_as_float(u << 16); }
; __device__ __forceinline__ float bfhi(unsigned u) { return __uint_as_float(u & 0xffff0000u); }
; __device__ __forceinline__ unsigned pk2(float lo, float hi) { f32x2_t v = {lo, hi}; bf16x2_t b = __builtin_convertvector(v, bf16x2_t); return __builtin_bit_cast(unsigned, b); }
; __device__ __forceinline__ void atomic_add_agent(float* p, float v) { (void)__hip_atomic_fetch_add(p, v, __ATOMIC_RELAXED, __HIP_MEMORY_SCOPE_AGENT); }
;     __device__ __forceinline__ void operator()(const f32x4 (&acc)[2][2][4][2], const pg8::Unit& u, int wr, int wc, int fr, int fq) const {
;     ...
;                 const int row = row0 + ai * 128 + m * 16; float s2 = 0.f;
; #pragma unroll
;                 for (int bj = 0; bj < 2; ++bj) {
;                     const size_t off = (size_t)row * 1024 + c0 + bj * 128;
;                     f32x4 x0, x1;
;                     if (xin) { x0 = *(const f32x4*)(xin + off); x1 = *(const f32x4*)(xin + off + 4); }
;                     else { const v4u xv = *(const v4u*)(xb + off); x0 = (f32x4){bflo(xv.x), bfhi(xv.x), bflo(xv.y), bfhi(xv.y)}; x1 = (f32x4){bflo(xv.z), bfhi(xv.z), bflo(xv.w), bfhi(xv.w)}; }
;                     const f32x4 n0 = x0 + acc[ai][bj][m][0], n1 = x1 + acc[ai][bj][m][1];
;                     if (xout) { *(f32x4*)(xout + off) = n0; *(f32x4*)(xout + off + 4) = n1; }
;                     else *(v4u*)(xb + off) = (v4u){pk2(n0[0], n0[1]), pk2(n0[2], n0[3]), pk2(n1[0], n1[1]), pk2(n1[2], n1[3])};
;                     s2 += ((n0[0] * n0[0] + n0[1] * n0[1]) + (n0[2] * n0[2] + n0[3] * n0[3])) + ((n1[0] * n1[0] + n1[1] * n1[1]) + (n1[2] * n1[2] + n1[3] * n1[3]));
;                 }
;                 if (ssq) { s2 += __shfl_xor(s2, 16); s2 += __shfl_xor(s2, 32); if (fq == 0) atomic_add_agent(ssq + row, s2); }
.LBB0_473:
	s_or_b64 exec, exec, s[2:3]
	v_or_b32_e32 v82, 48, v168
	s_waitcnt lgkmcnt(0)
	v_ashrrev_i32_e32 v83, 31, v82
	v_lshlrev_b64 v[84:85], 10, v[82:83]
	v_readlane_b32 s2, v255, 22
	v_lshl_add_u64 v[84:85], v[84:85], 0, v[166:167]
	v_readlane_b32 s3, v255, 23
	s_nop 1
	v_lshl_add_u64 v[88:89], v[84:85], 1, s[2:3]
	v_mov_b32_e32 v84, v76
	v_mov_b32_e32 v85, v77
	v_mov_b32_e32 v86, v74
	v_mov_b32_e32 v87, v75
	v_cvt_pk_bf16_f32 v74, v78, v79
	v_cvt_pk_bf16_f32 v75, v80, v81
	v_cvt_pk_bf16_f32 v76, v86, v87
	v_cvt_pk_bf16_f32 v77, v84, v85
	global_store_dwordx4 v[88:89], v[74:77], off
	s_nop 1
	v_mul_f32_e32 v74, v79, v79
	v_mul_f32_e32 v75, v81, v81
	v_fmac_f32_e32 v74, v78, v78
	v_fmac_f32_e32 v75, v80, v80
	v_add_f32_e32 v74, v74, v75
	v_mul_f32_e32 v75, v87, v87
	v_mul_f32_e32 v76, v85, v85
	v_fmac_f32_e32 v75, v86, v86
	v_fmac_f32_e32 v76, v84, v84
	v_add_f32_e32 v75, v75, v76
	v_add_f32_e32 v84, v74, v75
	v_mov_b32_e32 v74, v68
	v_mov_b32_e32 v75, v69
	v_mov_b32_e32 v76, v66
	v_mov_b32_e32 v77, v67
	v_cvt_pk_bf16_f32 v66, v70, v71
	v_cvt_pk_bf16_f32 v67, v72, v73
	v_cvt_pk_bf16_f32 v68, v76, v77
	v_cvt_pk_bf16_f32 v69, v74, v75
	global_store_dwordx4 v[88:89], v[66:69], off offset:256
	s_nop 1
	v_mul_f32_e32 v66, v71, v71
	v_mul_f32_e32 v67, v73, v73
	v_fmac_f32_e32 v66, v70, v70
	v_fmac_f32_e32 v67, v72, v72
	v_add_f32_e32 v66, v66, v67
	v_mul_f32_e32 v67, v77, v77
	v_mul_f32_e32 v68, v75, v75
	v_fmac_f32_e32 v67, v76, v76
	v_fmac_f32_e32 v68, v74, v74
	v_add_f32_e32 v67, v67, v68
	v_add_f32_e32 v66, v66, v67
	v_add_f32_e32 v66, v84, v66
	ds_bpermute_b32 v67, v116, v66
	s_waitcnt lgkmcnt(0)
	v_add_f32_e32 v66, v66, v67
	ds_bpermute_b32 v67, v117, v66
	s_and_saveexec_b64 s[2:3], s[0:1]
	s_cbranch_execz .LBB0_475
	v_readlane_b32 s20, v252, 60
	v_readlane_b32 s21, v252, 61
	s_waitcnt lgkmcnt(0)
	v_add_f32_e32 v66, v66, v67
	v_lshl_add_u64 v[68:69], v[82:83], 2, s[20:21]
	global_atomic_add_f32 v[68:69], v66, off
.LBB0_475:
	s_or_b64 exec, exec, s[2:3]
	v_add_u32_e32 v66, 0x80, v168
	s_waitcnt lgkmcnt(0)
	v_ashrrev_i32_e32 v67, 31, v66
	v_lshlrev_b64 v[68:69], 10, v[66:67]
	v_readlane_b32 s2, v255, 22
	v_lshl_add_u64 v[68:69], v[68:69], 0, v[166:167]
	v_readlane_b32 s3, v255, 23
	s_nop 1
	v_lshl_add_u64 v[72:73], v[68:69], 1, s[2:3]
	v_mov_b32_e32 v68, v60
	v_mov_b32_e32 v69, v61
	v_mov_b32_e32 v70, v58
	v_mov_b32_e32 v71, v59
	v_cvt_pk_bf16_f32 v58, v62, v63
	v_cvt_pk_bf16_f32 v59, v64, v65
	v_cvt_pk_bf16_f32 v60, v70, v71
	v_cvt_pk_bf16_f32 v61, v68, v69
	global_store_dwordx4 v[72:73], v[58:61], off
	s_nop 1
	v_mul_f32_e32 v58, v63, v63
	v_mul_f32_e32 v59, v65, v65
	v_fmac_f32_e32 v58, v62, v62
	v_fmac_f32_e32 v59, v64, v64
	v_add_f32_e32 v58, v58, v59
	v_mul_f32_e32 v59, v71, v71
	v_mul_f32_e32 v60, v69, v69
	v_fmac_f32_e32 v59, v70, v70
	v_fmac_f32_e32 v60, v68, v68
	v_add_f32_e32 v59, v59, v60
	v_add_f32_e32 v68, v58, v59
	v_mov_b32_e32 v58, v52
	v_mov_b32_e32 v59, v53
	v_mov_b32_e32 v60, v50
	v_mov_b32_e32 v61, v51
	v_cvt_pk_bf16_f32 v50, v54, v55
	v_cvt_pk_bf16_f32 v51, v56, v57
	v_cvt_pk_bf16_f32 v52, v60, v61
	v_cvt_pk_bf16_f32 v53, v58, v59
	global_store_dwordx4 v[72:73], v[50:53], off offset:256
	s_nop 1
	v_mul_f32_e32 v50, v55, v55
	v_mul_f32_e32 v51, v57, v57
	v_fmac_f32_e32 v50, v54, v54
	v_fmac_f32_e32 v51, v56, v56
	v_add_f32_e32 v50, v50, v51
	v_mul_f32_e32 v51, v61, v61
	v_mul_f32_e32 v52, v59, v59
	v_fmac_f32_e32 v51, v60, v60
	v_fmac_f32_e32 v52, v58, v58
	v_add_f32_e32 v51, v51, v52
	v_add_f32_e32 v50, v50, v51
	v_add_f32_e32 v50, v68, v50
	ds_bpermute_b32 v51, v116, v50
	s_waitcnt lgkmcnt(0)
	v_add_f32_e32 v50, v50, v51
	ds_bpermute_b32 v51, v117, v50
	s_and_saveexec_b64 s[2:3], s[0:1]
	s_cbranch_execz .LBB0_477
	v_readlane_b32 s20, v252, 60
	v_readlane_b32 s21, v252, 61
	s_waitcnt lgkmcnt(0)
	v_add_f32_e32 v50, v50, v51
	v_lshl_add_u64 v[52:53], v[66:67], 2, s[20:21]
	global_atomic_add_f32 v[52:53], v50, off
; __device__ __forceinline__ float bflo(unsigned u) { return __uint_as_float(u << 16); }
; __device__ __forceinline__ float bfhi(unsigned u) { return __uint_as_float(u & 0xffff0000u); }
; __device__ __forceinline__ unsigned pk2(float lo, float hi) { f32x2_t v = {lo, hi}; bf16x2_t b = __builtin_convertvector(v, bf16x2_t); return __builtin_bit_cast(unsigned, b); }
; __device__ __forceinline__ void atomic_add_agent(float* p, float v) { (void)__hip_atomic_fetch_add(p, v, __ATOMIC_RELAXED, __HIP_MEMORY_SCOPE_AGENT); }
;     __device__ __forceinline__ void operator()(const f32x4 (&acc)[2][2][4][2], const pg8::Unit& u, int wr, int wc, int fr, int fq) const {
;     ...
;                 const int row = row0 + ai * 128 + m * 16; float s2 = 0.f;
; #pragma unroll
;                 for (int bj = 0; bj < 2; ++bj) {
;                     const size_t off = (size_t)row * 1024 + c0 + bj * 128;
;                     f32x4 x0, x1;
;                     if (xin) { x0 = *(const f32x4*)(xin + off); x1 = *(const f32x4*)(xin + off + 4); }
;                     else { const v4u xv = *(const v4u*)(xb + off); x0 = (f32x4){bflo(xv.x), bfhi(xv.x), bflo(xv.y), bfhi(xv.y)}; x1 = (f32x4){bflo(xv.z), bfhi(xv.z), bflo(xv.w), bfhi(xv.w)}; }
;                     const f32x4 n0 = x0 + acc[ai][bj][m][0], n1 = x1 + acc[ai][bj][m][1];
;                     if (xout) { *(f32x4*)(xout + off) = n0; *(f32x4*)(xout + off + 4) = n1; }
;                     else *(v4u*)(xb + off) = (v4u){pk2(n0[0], n0[1]), pk2(n0[2], n0[3]), pk2(n1[0], n1[1]), pk2(n1[2], n1[3])};
;                     s2 += ((n0[0] * n0[0] + n0[1] * n0[1]) + (n0[2] * n0[2] + n0[3] * n0[3])) + ((n1[0] * n1[0] + n1[1] * n1[1]) + (n1[2] * n1[2] + n1[3] * n1[3]));
;                 }
;                 if (ssq) { s2 += __shfl_xor(s2, 16); s2 += __shfl_xor(s2, 32); if (fq == 0) atomic_add_agent(ssq + row, s2); }
.LBB0_477:
	s_or_b64 exec, exec, s[2:3]
	v_add_u32_e32 v50, 0x90, v168
	s_waitcnt lgkmcnt(0)
	v_ashrrev_i32_e32 v51, 31, v50
	v_lshlrev_b64 v[52:53], 10, v[50:51]
	v_readlane_b32 s2, v255, 22
	v_lshl_add_u64 v[52:53], v[52:53], 0, v[166:167]
	v_readlane_b32 s3, v255, 23
	s_nop 1
	v_lshl_add_u64 v[56:57], v[52:53], 1, s[2:3]
	v_mov_b32_e32 v52, v44
	v_mov_b32_e32 v53, v45
	v_mov_b32_e32 v54, v42
	v_mov_b32_e32 v55, v43
	v_cvt_pk_bf16_f32 v42, v46, v47
	v_cvt_pk_bf16_f32 v43, v48, v49
	v_cvt_pk_bf16_f32 v44, v54, v55
	v_cvt_pk_bf16_f32 v45, v52, v53
	global_store_dwordx4 v[56:57], v[42:45], off
	s_nop 1
	v_mul_f32_e32 v42, v47, v47
	v_mul_f32_e32 v43, v49, v49
	v_fmac_f32_e32 v42, v46, v46
	v_fmac_f32_e32 v43, v48, v48
	v_add_f32_e32 v42, v42, v43
	v_mul_f32_e32 v43, v55, v55
	v_mul_f32_e32 v44, v53, v53
	v_fmac_f32_e32 v43, v54, v54
	v_fmac_f32_e32 v44, v52, v52
	v_add_f32_e32 v43, v43, v44
	v_add_f32_e32 v52, v42, v43
	v_mov_b32_e32 v42, v36
	v_mov_b32_e32 v43, v37
	v_mov_b32_e32 v44, v34
	v_mov_b32_e32 v45, v35
	v_cvt_pk_bf16_f32 v34, v38, v39
	v_cvt_pk_bf16_f32 v35, v40, v41
	v_cvt_pk_bf16_f32 v36, v44, v45
	v_cvt_pk_bf16_f32 v37, v42, v43
	global_store_dwordx4 v[56:57], v[34:37], off offset:256
	s_nop 1
	v_mul_f32_e32 v34, v39, v39
	v_mul_f32_e32 v35, v41, v41
	v_fmac_f32_e32 v34, v38, v38
	v_fmac_f32_e32 v35, v40, v40
	v_add_f32_e32 v34, v34, v35
	v_mul_f32_e32 v35, v45, v45
	v_mul_f32_e32 v36, v43, v43
	v_fmac_f32_e32 v35, v44, v44
	v_fmac_f32_e32 v36, v42, v42
	v_add_f32_e32 v35, v35, v36
	v_add_f32_e32 v34, v34, v35
	v_add_f32_e32 v34, v52, v34
	ds_bpermute_b32 v35, v116, v34
	s_waitcnt lgkmcnt(0)
	v_add_f32_e32 v34, v34, v35
	ds_bpermute_b32 v35, v117, v34
	s_and_saveexec_b64 s[2:3], s[0:1]
	s_cbranch_execz .LBB0_479
	v_readlane_b32 s20, v252, 60
	v_readlane_b32 s21, v252, 61
	s_waitcnt lgkmcnt(0)
	v_add_f32_e32 v34, v34, v35
	v_lshl_add_u64 v[36:37], v[50:51], 2, s[20:21]
	global_atomic_add_f32 v[36:37], v34, off
.LBB0_479:
	s_or_b64 exec, exec, s[2:3]
	v_add_u32_e32 v34, 0xa0, v168
	s_waitcnt lgkmcnt(0)
	v_ashrrev_i32_e32 v35, 31, v34
	v_lshlrev_b64 v[36:37], 10, v[34:35]
	v_readlane_b32 s2, v255, 22
	v_lshl_add_u64 v[36:37], v[36:37], 0, v[166:167]
	v_readlane_b32 s3, v255, 23
	s_nop 1
	v_lshl_add_u64 v[40:41], v[36:37], 1, s[2:3]
	v_mov_b32_e32 v36, v28
	v_mov_b32_e32 v37, v29
	v_mov_b32_e32 v38, v26
	v_mov_b32_e32 v39, v27
	v_cvt_pk_bf16_f32 v26, v30, v31
	v_cvt_pk_bf16_f32 v27, v32, v33
	v_cvt_pk_bf16_f32 v28, v38, v39
	v_cvt_pk_bf16_f32 v29, v36, v37
	global_store_dwordx4 v[40:41], v[26:29], off
	s_nop 1
	v_mul_f32_e32 v26, v31, v31
	v_mul_f32_e32 v27, v33, v33
	v_fmac_f32_e32 v26, v30, v30
	v_fmac_f32_e32 v27, v32, v32
	v_add_f32_e32 v26, v26, v27
	v_mul_f32_e32 v27, v39, v39
	v_mul_f32_e32 v28, v37, v37
	v_fmac_f32_e32 v27, v38, v38
	v_fmac_f32_e32 v28, v36, v36
	v_add_f32_e32 v27, v27, v28
	v_add_f32_e32 v36, v26, v27
	v_mov_b32_e32 v26, v20
	v_mov_b32_e32 v27, v21
	v_mov_b32_e32 v28, v18
	v_mov_b32_e32 v29, v19
	v_cvt_pk_bf16_f32 v18, v22, v23
	v_cvt_pk_bf16_f32 v19, v24, v25
	v_cvt_pk_bf16_f32 v20, v28, v29
	v_cvt_pk_bf16_f32 v21, v26, v27
	global_store_dwordx4 v[40:41], v[18:21], off offset:256
	s_nop 1
	v_mul_f32_e32 v18, v23, v23
	v_mul_f32_e32 v19, v25, v25
	v_fmac_f32_e32 v18, v22, v22
	v_fmac_f32_e32 v19, v24, v24
	v_add_f32_e32 v18, v18, v19
	v_mul_f32_e32 v19, v29, v29
	v_mul_f32_e32 v20, v27, v27
	v_fmac_f32_e32 v19, v28, v28
	v_fmac_f32_e32 v20, v26, v26
	v_add_f32_e32 v19, v19, v20
	v_add_f32_e32 v18, v18, v19
	v_add_f32_e32 v18, v36, v18
	ds_bpermute_b32 v19, v116, v18
	s_waitcnt lgkmcnt(0)
	v_add_f32_e32 v18, v18, v19
	ds_bpermute_b32 v19, v117, v18
	s_and_saveexec_b64 s[2:3], s[0:1]
	s_cbranch_execz .LBB0_481
	v_readlane_b32 s20, v252, 60
	v_readlane_b32 s21, v252, 61
	s_waitcnt lgkmcnt(0)
	v_add_f32_e32 v18, v18, v19
	v_lshl_add_u64 v[20:21], v[34:35], 2, s[20:21]
	global_atomic_add_f32 v[20:21], v18, off
.LBB0_481:
	s_or_b64 exec, exec, s[2:3]
	v_add_u32_e32 v18, 0xb0, v168
	s_waitcnt lgkmcnt(0)
	v_ashrrev_i32_e32 v19, 31, v18
	v_lshlrev_b64 v[20:21], 10, v[18:19]
	v_readlane_b32 s2, v255, 22
	v_lshl_add_u64 v[20:21], v[20:21], 0, v[166:167]
	v_readlane_b32 s3, v255, 23
	s_nop 1
	v_lshl_add_u64 v[24:25], v[20:21], 1, s[2:3]
	v_mov_b32_e32 v20, v12
	v_mov_b32_e32 v21, v13
	v_mov_b32_e32 v22, v10
	v_mov_b32_e32 v23, v11
	v_cvt_pk_bf16_f32 v10, v14, v15
	v_cvt_pk_bf16_f32 v11, v16, v17
	v_cvt_pk_bf16_f32 v12, v22, v23
	v_cvt_pk_bf16_f32 v13, v20, v21
	global_store_dwordx4 v[24:25], v[10:13], off
	s_nop 1
	v_mul_f32_e32 v10, v15, v15
	v_mul_f32_e32 v11, v17, v17
	v_fmac_f32_e32 v10, v14, v14
	v_fmac_f32_e32 v11, v16, v16
	v_add_f32_e32 v10, v10, v11
	v_mul_f32_e32 v11, v23, v23
	v_mul_f32_e32 v12, v21, v21
	v_fmac_f32_e32 v11, v22, v22
	v_fmac_f32_e32 v12, v20, v20
	v_add_f32_e32 v11, v11, v12
	v_add_f32_e32 v20, v10, v11
	v_mov_b32_e32 v10, v4
	v_mov_b32_e32 v11, v5
	v_mov_b32_e32 v12, v2
	v_mov_b32_e32 v13, v3
	v_cvt_pk_bf16_f32 v2, v6, v7
	v_cvt_pk_bf16_f32 v3, v8, v9
	v_cvt_pk_bf16_f32 v4, v12, v13
	v_cvt_pk_bf16_f32 v5, v10, v11
	global_store_dwordx4 v[24:25], v[2:5], off offset:256
	s_nop 1
	v_mul_f32_e32 v2, v7, v7
	v_mul_f32_e32 v3, v9, v9
	v_fmac_f32_e32 v2, v6, v6
	v_fmac_f32_e32 v3, v8, v8
	v_add_f32_e32 v2, v2, v3
	v_mul_f32_e32 v3, v13, v13
	v_mul_f32_e32 v4, v11, v11
	v_fmac_f32_e32 v3, v12, v12
	v_fmac_f32_e32 v4, v10, v10
	v_add_f32_e32 v3, v3, v4
	v_add_f32_e32 v2, v2, v3
	v_add_f32_e32 v2, v20, v2
	ds_bpermute_b32 v3, v116, v2
	s_waitcnt lgkmcnt(0)
	v_add_f32_e32 v2, v2, v3
	ds_bpermute_b32 v3, v117, v2
	s_and_saveexec_b64 s[2:3], s[0:1]
	s_cbranch_execz .LBB0_483
	v_readlane_b32 s20, v252, 60
	v_readlane_b32 s21, v252, 61
	s_waitcnt lgkmcnt(0)
	v_add_f32_e32 v2, v2, v3
	v_lshl_add_u64 v[4:5], v[18:19], 2, s[20:21]
	global_atomic_add_f32 v[4:5], v2, off

; __device__ __forceinline__ float bflo(unsigned u) { return __uint_as_float(u << 16); }
; __device__ __forceinline__ float bfhi(unsigned u) { return __uint_as_float(u & 0xffff0000u); }
; template <class Epi, class Sched, bool ALIGN_EPI = false, bool SP2 = false>
; __device__ __forceinline__ void gemm_phase(PG8_LAS unsigned char* lds, const Gemm g, const Sched& S, const Epi& E) {
;     ...
;         for (int a = 0; a < 2; ++a)
; #pragma unroll
;             for (int b = 0; b < 2; ++b)
; #pragma unroll
;                 for (int m = 0; m < 4; ++m)
; #pragma unroll
;                     for (int n = 0; n < 2; ++n) acc[a][b][m][n] = (f32x4){0.f, 0.f, 0.f, 0.f};
;     __device__ __forceinline__ void operator()(const f32x4 (&acc)[2][2][4][2], const pg8::Unit& u, int wr, int wc, int fr, int fq) const {
;     ...
;                     const size_t off = (size_t)row * 1024 + c0 + bj * 128;
;                     f32x4 x0, x1;
;                     if (xin) { x0 = *(const f32x4*)(xin + off); x1 = *(const f32x4*)(xin + off + 4); }
;                     else { const v4u xv = *(const v4u*)(xb + off); x0 = (f32x4){bflo(xv.x), bfhi(xv.x), bflo(xv.y), bfhi(xv.y)}; x1 = (f32x4){bflo(xv.z), bfhi(xv.z), bflo(xv.w), bfhi(xv.w)}; }
.LBB0_827:
	s_ashr_i32 s13, s12, 31
	s_lshl_b64 s[14:15], s[12:13], 19
	s_add_u32 s14, s50, s14
	s_addc_u32 s15, s51, s15
	s_and_b64 s[18:19], s[4:5], exec
	s_cselect_b32 s13, s15, s3
	s_cselect_b32 s39, s14, s2
	s_ashr_i32 s11, s10, 31
	s_lshl_b64 s[18:19], s[10:11], 19
	v_readlane_b32 s22, v254, 29
	v_readlane_b32 s23, v254, 30
	s_add_u32 s18, s22, s18
	s_addc_u32 s19, s23, s19
	s_and_b64 s[22:23], s[4:5], exec
	s_cselect_b32 s11, s19, s21
	s_cselect_b32 s40, s18, s20
	s_add_u32 s2, s2, 0x40080
	s_addc_u32 s3, s3, 0
	s_add_u32 s41, s20, 0x100
	v_mov_b32_e32 v2, 0
	s_addc_u32 s42, s21, 0
	s_mov_b32 s43, -2
	s_waitcnt lgkmcnt(0)
	v_mov_b32_e32 v3, v2
	v_mov_b32_e32 v4, v2
	v_mov_b32_e32 v5, v2
	v_mov_b32_e32 v6, v2
	v_mov_b32_e32 v7, v2
	v_mov_b32_e32 v8, v2
	v_mov_b32_e32 v9, v2
	v_mov_b32_e32 v18, v2
	v_mov_b32_e32 v19, v2
	v_mov_b32_e32 v20, v2
	v_mov_b32_e32 v21, v2
	v_mov_b32_e32 v22, v2
	v_mov_b32_e32 v23, v2
	v_mov_b32_e32 v24, v2
	v_mov_b32_e32 v25, v2
	v_mov_b32_e32 v34, v2
	v_mov_b32_e32 v35, v2
	v_mov_b32_e32 v36, v2
	v_mov_b32_e32 v37, v2
	v_mov_b32_e32 v38, v2
	v_mov_b32_e32 v39, v2
	v_mov_b32_e32 v40, v2
	v_mov_b32_e32 v41, v2
	s_waitcnt vmcnt(0)
	v_mov_b32_e32 v50, v2
	v_mov_b32_e32 v51, v2
	v_mov_b32_e32 v52, v2
	v_mov_b32_e32 v53, v2
	v_mov_b32_e32 v54, v2
	v_mov_b32_e32 v55, v2
	v_mov_b32_e32 v56, v2
	v_mov_b32_e32 v57, v2
	v_mov_b32_e32 v10, v2
	v_mov_b32_e32 v11, v2
	v_mov_b32_e32 v12, v2
	v_mov_b32_e32 v13, v2
	v_mov_b32_e32 v14, v2
	v_mov_b32_e32 v15, v2
	v_mov_b32_e32 v16, v2
	v_mov_b32_e32 v17, v2
	v_mov_b32_e32 v26, v2
	v_mov_b32_e32 v27, v2
	v_mov_b32_e32 v28, v2
	v_mov_b32_e32 v29, v2
	v_mov_b32_e32 v30, v2
	v_mov_b32_e32 v31, v2
	v_mov_b32_e32 v32, v2
	v_mov_b32_e32 v33, v2
	v_mov_b32_e32 v42, v2
	v_mov_b32_e32 v43, v2
	v_mov_b32_e32 v44, v2
	v_mov_b32_e32 v45, v2
	v_mov_b32_e32 v46, v2
	v_mov_b32_e32 v47, v2
	v_mov_b32_e32 v48, v2
	v_mov_b32_e32 v49, v2
	v_mov_b32_e32 v58, v2
	v_mov_b32_e32 v59, v2
	v_mov_b32_e32 v60, v2
	v_mov_b32_e32 v61, v2
	v_mov_b32_e32 v62, v2
	v_mov_b32_e32 v63, v2
	v_mov_b32_e32 v64, v2
	v_mov_b32_e32 v65, v2
	v_mov_b32_e32 v66, v2
	v_mov_b32_e32 v67, v2
	v_mov_b32_e32 v68, v2
	v_mov_b32_e32 v69, v2
	v_mov_b32_e32 v70, v2
	v_mov_b32_e32 v71, v2
	v_mov_b32_e32 v72, v2
	v_mov_b32_e32 v73, v2
	v_mov_b32_e32 v82, v2
	v_mov_b32_e32 v83, v2
	v_mov_b32_e32 v84, v2
	v_mov_b32_e32 v85, v2
	v_mov_b32_e32 v86, v2
	v_mov_b32_e32 v87, v2
	v_mov_b32_e32 v88, v2
	v_mov_b32_e32 v89, v2
	v_mov_b32_e32 v98, v2
	v_mov_b32_e32 v99, v2
	v_mov_b32_e32 v100, v2
	v_mov_b32_e32 v101, v2
	v_mov_b32_e32 v102, v2
	v_mov_b32_e32 v103, v2
	v_mov_b32_e32 v104, v2
	v_mov_b32_e32 v105, v2
	v_mov_b32_e32 v114, v2
	v_mov_b32_e32 v115, v2
	v_mov_b32_e32 v116, v2
	v_mov_b32_e32 v117, v2
	v_mov_b32_e32 v118, v2
	v_mov_b32_e32 v119, v2
	v_mov_b32_e32 v120, v2
	v_mov_b32_e32 v121, v2
	v_mov_b32_e32 v74, v2
	v_mov_b32_e32 v75, v2
	v_mov_b32_e32 v76, v2
	v_mov_b32_e32 v77, v2
	v_mov_b32_e32 v78, v2
	v_mov_b32_e32 v79, v2
	v_mov_b32_e32 v80, v2
	v_mov_b32_e32 v81, v2
	v_mov_b32_e32 v90, v2
	v_mov_b32_e32 v91, v2
	v_mov_b32_e32 v92, v2
	v_mov_b32_e32 v93, v2
	v_mov_b32_e32 v94, v2
	v_mov_b32_e32 v95, v2
	v_mov_b32_e32 v96, v2
	v_mov_b32_e32 v97, v2
	v_mov_b32_e32 v106, v2
	v_mov_b32_e32 v107, v2
	v_mov_b32_e32 v108, v2
	v_mov_b32_e32 v109, v2
	v_mov_b32_e32 v110, v2
	v_mov_b32_e32 v111, v2
	v_mov_b32_e32 v112, v2
	v_mov_b32_e32 v113, v2
	v_mov_b32_e32 v122, v2
	v_mov_b32_e32 v123, v2
	v_mov_b32_e32 v124, v2
	v_mov_b32_e32 v125, v2
	v_mov_b32_e32 v126, v2
	v_mov_b32_e32 v127, v2
	v_mov_b32_e32 v128, v2
	v_mov_b32_e32 v129, v2
	v_readlane_b32 s100, v255, 22
	v_readlane_b32 s101, v255, 23
	v_lshl_add_u32 v196, s38, 8, v1
	v_lshl_or_b32 v198, s37, 8, v170
	v_ashrrev_i32_e32 v197, 31, v196
	v_ashrrev_i32_e32 v199, 31, v198
	v_lshlrev_b64 v[200:201], 10, v[196:197]
	v_lshl_add_u64 v[200:201], v[200:201], 0, v[198:199]
	v_lshl_add_u64 v[200:201], v[200:201], 1, s[100:101]
	v_mov_b32_e32 v217, 0
	v_mov_b32_e32 v216, 0x8000
	v_lshl_add_u64 v[202:203], v[200:201], 0, v[216:217]
	v_mov_b32_e32 v216, 0x10000
	v_lshl_add_u64 v[204:205], v[200:201], 0, v[216:217]
	v_mov_b32_e32 v216, 0x18000
	v_lshl_add_u64 v[206:207], v[200:201], 0, v[216:217]
	v_mov_b32_e32 v216, 0x40000
	v_lshl_add_u64 v[208:209], v[200:201], 0, v[216:217]
	v_mov_b32_e32 v216, 0x48000
	v_lshl_add_u64 v[210:211], v[200:201], 0, v[216:217]
	v_mov_b32_e32 v216, 0x50000
	v_lshl_add_u64 v[212:213], v[200:201], 0, v[216:217]
	v_mov_b32_e32 v216, 0x58000
	v_lshl_add_u64 v[214:215], v[200:201], 0, v[216:217]
	global_load_dwordx4 v[122:125], v[200:201], off
	global_load_dwordx4 v[114:117], v[200:201], off offset:256
	global_load_dwordx4 v[106:109], v[202:203], off
	global_load_dwordx4 v[98:101], v[202:203], off offset:256
	global_load_dwordx4 v[90:93], v[204:205], off
	global_load_dwordx4 v[82:85], v[204:205], off offset:256
	global_load_dwordx4 v[74:77], v[206:207], off
	global_load_dwordx4 v[66:69], v[206:207], off offset:256
	global_load_dwordx4 v[58:61], v[208:209], off
	global_load_dwordx4 v[50:53], v[208:209], off offset:256
	global_load_dwordx4 v[42:45], v[210:211], off
	global_load_dwordx4 v[34:37], v[210:211], off offset:256
	global_load_dwordx4 v[26:29], v[212:213], off
	global_load_dwordx4 v[18:21], v[212:213], off offset:256
	global_load_dwordx4 v[10:13], v[214:215], off
	global_load_dwordx4 v[2:5], v[214:215], off offset:256
	s_waitcnt vmcnt(0)
; __device__ __forceinline__ float bflo(unsigned u) { return __uint_as_float(u << 16); }
; __device__ __forceinline__ float bfhi(unsigned u) { return __uint_as_float(u & 0xffff0000u); }
;     __device__ __forceinline__ void operator()(const f32x4 (&acc)[2][2][4][2], const pg8::Unit& u, int wr, int wc, int fr, int fq) const {
;     ...
;                     f32x4 x0, x1;
;                     if (xin) { x0 = *(const f32x4*)(xin + off); x1 = *(const f32x4*)(xin + off + 4); }
;                     else { const v4u xv = *(const v4u*)(xb + off); x0 = (f32x4){bflo(xv.x), bfhi(xv.x), bflo(xv.y), bfhi(xv.y)}; x1 = (f32x4){bflo(xv.z), bfhi(xv.z), bflo(xv.w), bfhi(xv.w)}; }
;                     const f32x4 n0 = x0 + acc[ai][bj][m][0], n1 = x1 + acc[ai][bj][m][1];
	v_lshlrev_b32_e32 v126, 16, v122
	v_and_b32_e32 v127, 0xffff0000, v122
	v_lshlrev_b32_e32 v128, 16, v123
	v_and_b32_e32 v129, 0xffff0000, v123
	v_lshlrev_b32_e32 v122, 16, v124
	v_and_b32_e32 v123, 0xffff0000, v124
	v_lshlrev_b32_e32 v124, 16, v125
	v_and_b32_e32 v125, 0xffff0000, v125
	v_lshlrev_b32_e32 v118, 16, v114
	v_and_b32_e32 v119, 0xffff0000, v114
	v_lshlrev_b32_e32 v120, 16, v115
	v_and_b32_e32 v121, 0xffff0000, v115
	v_lshlrev_b32_e32 v114, 16, v116
	v_and_b32_e32 v115, 0xffff0000, v116
	v_lshlrev_b32_e32 v116, 16, v117
	v_and_b32_e32 v117, 0xffff0000, v117
	v_lshlrev_b32_e32 v110, 16, v106
	v_and_b32_e32 v111, 0xffff0000, v106
	v_lshlrev_b32_e32 v112, 16, v107
	v_and_b32_e32 v113, 0xffff0000, v107
	v_lshlrev_b32_e32 v106, 16, v108
	v_and_b32_e32 v107, 0xffff0000, v108
	v_lshlrev_b32_e32 v108, 16, v109
	v_and_b32_e32 v109, 0xffff0000, v109
	v_lshlrev_b32_e32 v102, 16, v98
	v_and_b32_e32 v103, 0xffff0000, v98
	v_lshlrev_b32_e32 v104, 16, v99
	v_and_b32_e32 v105, 0xffff0000, v99
	v_lshlrev_b32_e32 v98, 16, v100
	v_and_b32_e32 v99, 0xffff0000, v100
	v_lshlrev_b32_e32 v100, 16, v101
	v_and_b32_e32 v101, 0xffff0000, v101
	v_lshlrev_b32_e32 v94, 16, v90
	v_and_b32_e32 v95, 0xffff0000, v90
	v_lshlrev_b32_e32 v96, 16, v91
	v_and_b32_e32 v97, 0xffff0000, v91
	v_lshlrev_b32_e32 v90, 16, v92
	v_and_b32_e32 v91, 0xffff0000, v92
	v_lshlrev_b32_e32 v92, 16, v93
	v_and_b32_e32 v93, 0xffff0000, v93
	v_lshlrev_b32_e32 v86, 16, v82
	v_and_b32_e32 v87, 0xffff0000, v82
	v_lshlrev_b32_e32 v88, 16, v83
	v_and_b32_e32 v89, 0xffff0000, v83
	v_lshlrev_b32_e32 v82, 16, v84
	v_and_b32_e32 v83, 0xffff0000, v84
	v_lshlrev_b32_e32 v84, 16, v85
	v_and_b32_e32 v85, 0xffff0000, v85
	v_lshlrev_b32_e32 v78, 16, v74
	v_and_b32_e32 v79, 0xffff0000, v74
	v_lshlrev_b32_e32 v80, 16, v75
	v_and_b32_e32 v81, 0xffff0000, v75
	v_lshlrev_b32_e32 v74, 16, v76
	v_and_b32_e32 v75, 0xffff0000, v76
	v_lshlrev_b32_e32 v76, 16, v77
	v_and_b32_e32 v77, 0xffff0000, v77
	v_lshlrev_b32_e32 v70, 16, v66
	v_and_b32_e32 v71, 0xffff0000, v66
	v_lshlrev_b32_e32 v72, 16, v67
	v_and_b32_e32 v73, 0xffff0000, v67
	v_lshlrev_b32_e32 v66, 16, v68
	v_and_b32_e32 v67, 0xffff0000, v68
	v_lshlrev_b32_e32 v68, 16, v69
	v_and_b32_e32 v69, 0xffff0000, v69
	v_lshlrev_b32_e32 v62, 16, v58
	v_and_b32_e32 v63, 0xffff0000, v58
	v_lshlrev_b32_e32 v64, 16, v59
	v_and_b32_e32 v65, 0xffff0000, v59
	v_lshlrev_b32_e32 v58, 16, v60
	v_and_b32_e32 v59, 0xffff0000, v60
	v_lshlrev_b32_e32 v60, 16, v61
	v_and_b32_e32 v61, 0xffff0000, v61
	v_lshlrev_b32_e32 v54, 16, v50
	v_and_b32_e32 v55, 0xffff0000, v50
	v_lshlrev_b32_e32 v56, 16, v51
	v_and_b32_e32 v57, 0xffff0000, v51
	v_lshlrev_b32_e32 v50, 16, v52
	v_and_b32_e32 v51, 0xffff0000, v52
	v_lshlrev_b32_e32 v52, 16, v53
	v_and_b32_e32 v53, 0xffff0000, v53
	v_lshlrev_b32_e32 v46, 16, v42
	v_and_b32_e32 v47, 0xffff0000, v42
	v_lshlrev_b32_e32 v48, 16, v43
	v_and_b32_e32 v49, 0xffff0000, v43
	v_lshlrev_b32_e32 v42, 16, v44
	v_and_b32_e32 v43, 0xffff0000, v44
	v_lshlrev_b32_e32 v44, 16, v45
	v_and_b32_e32 v45, 0xffff0000, v45
	v_lshlrev_b32_e32 v38, 16, v34
	v_and_b32_e32 v39, 0xffff0000, v34
	v_lshlrev_b32_e32 v40, 16, v35
	v_and_b32_e32 v41, 0xffff0000, v35
	v_lshlrev_b32_e32 v34, 16, v36
	v_and_b32_e32 v35, 0xffff0000, v36
	v_lshlrev_b32_e32 v36, 16, v37
	v_and_b32_e32 v37, 0xffff0000, v37
	v_lshlrev_b32_e32 v30, 16, v26
	v_and_b32_e32 v31, 0xffff0000, v26
	v_lshlrev_b32_e32 v32, 16, v27
	v_and_b32_e32 v33, 0xffff0000, v27
	v_lshlrev_b32_e32 v26, 16, v28
	v_and_b32_e32 v27, 0xffff0000, v28
	v_lshlrev_b32_e32 v28, 16, v29
	v_and_b32_e32 v29, 0xffff0000, v29
	v_lshlrev_b32_e32 v22, 16, v18
	v_and_b32_e32 v23, 0xffff0000, v18
	v_lshlrev_b32_e32 v24, 16, v19
	v_and_b32_e32 v25, 0xffff0000, v19
	v_lshlrev_b32_e32 v18, 16, v20
	v_and_b32_e32 v19, 0xffff0000, v20
	v_lshlrev_b32_e32 v20, 16, v21
	v_and_b32_e32 v21, 0xffff0000, v21
	v_lshlrev_b32_e32 v14, 16, v10
	v_and_b32_e32 v15, 0xffff0000, v10
	v_lshlrev_b32_e32 v16, 16, v11
	v_and_b32_e32 v17, 0xffff0000, v11
	v_lshlrev_b32_e32 v10, 16, v12
	v_and_b32_e32 v11, 0xffff0000, v12
	v_lshlrev_b32_e32 v12, 16, v13
	v_and_b32_e32 v13, 0xffff0000, v13
	v_lshlrev_b32_e32 v6, 16, v2
	v_and_b32_e32 v7, 0xffff0000, v2
	v_lshlrev_b32_e32 v8, 16, v3
	v_and_b32_e32 v9, 0xffff0000, v3
	v_lshlrev_b32_e32 v2, 16, v4
	v_and_b32_e32 v3, 0xffff0000, v4
	v_lshlrev_b32_e32 v4, 16, v5
	v_and_b32_e32 v5, 0xffff0000, v5

; __device__ __forceinline__ float bflo(unsigned u) { return __uint_as_float(u << 16); }
; __device__ __forceinline__ float bfhi(unsigned u) { return __uint_as_float(u & 0xffff0000u); }
; __device__ __forceinline__ unsigned pk2(float lo, float hi) { f32x2_t v = {lo, hi}; bf16x2_t b = __builtin_convertvector(v, bf16x2_t); return __builtin_bit_cast(unsigned, b); }
; __device__ __forceinline__ void atomic_add_agent(float* p, float v) { (void)__hip_atomic_fetch_add(p, v, __ATOMIC_RELAXED, __HIP_MEMORY_SCOPE_AGENT); }
;     __device__ __forceinline__ void operator()(const f32x4 (&acc)[2][2][4][2], const pg8::Unit& u, int wr, int wc, int fr, int fq) const {
;         const int row0 = u.pm * 256 + wr * 64 + fr; const int c0 = u.pn * 256 + wc * 32 + 8 * fq;
; #pragma unroll
;         for (int ai = 0; ai < 2; ++ai)
; #pragma unroll
;             for (int m = 0; m < 4; ++m) {
;                 const int row = row0 + ai * 128 + m * 16; float s2 = 0.f;
; #pragma unroll
;                 for (int bj = 0; bj < 2; ++bj) {
;                     const size_t off = (size_t)row * 1024 + c0 + bj * 128;
;                     f32x4 x0, x1;
;                     if (xin) { x0 = *(const f32x4*)(xin + off); x1 = *(const f32x4*)(xin + off + 4); }
;                     else { const v4u xv = *(const v4u*)(xb + off); x0 = (f32x4){bflo(xv.x), bfhi(xv.x), bflo(xv.y), bfhi(xv.y)}; x1 = (f32x4){bflo(xv.z), bfhi(xv.z), bflo(xv.w), bfhi(xv.w)}; }
;                     const f32x4 n0 = x0 + acc[ai][bj][m][0], n1 = x1 + acc[ai][bj][m][1];
;                     if (xout) { *(f32x4*)(xout + off) = n0; *(f32x4*)(xout + off + 4) = n1; }
;                     else *(v4u*)(xb + off) = (v4u){pk2(n0[0], n0[1]), pk2(n0[2], n0[3]), pk2(n1[0], n1[1]), pk2(n1[2], n1[3])};
;                     s2 += ((n0[0] * n0[0] + n0[1] * n0[1]) + (n0[2] * n0[2] + n0[3] * n0[3])) + ((n1[0] * n1[0] + n1[1] * n1[1]) + (n1[2] * n1[2] + n1[3] * n1[3]));
;                 }
;                 if (ssq) { s2 += __shfl_xor(s2, 16); s2 += __shfl_xor(s2, 32); if (fq == 0) atomic_add_agent(ssq + row, s2); }
.LBB0_831:
	v_lshl_add_u32 v168, s38, 8, v1
	v_lshl_or_b32 v166, s37, 8, v170
	v_ashrrev_i32_e32 v169, 31, v168
	v_ashrrev_i32_e32 v167, 31, v166
	v_lshlrev_b64 v[150:151], 10, v[168:169]
	v_lshl_add_u64 v[150:151], v[150:151], 0, v[166:167]
	v_lshl_add_u64 v[154:155], v[150:151], 1, s[54:55]
	v_mov_b32_e32 v150, v124
	v_mov_b32_e32 v151, v125
	v_mov_b32_e32 v152, v122
	v_mov_b32_e32 v153, v123
	v_cvt_pk_bf16_f32 v122, v126, v127
	v_cvt_pk_bf16_f32 v123, v128, v129
	v_cvt_pk_bf16_f32 v124, v152, v153
	v_cvt_pk_bf16_f32 v125, v150, v151
	global_store_dwordx4 v[154:155], v[122:125], off
	s_nop 1
	v_mul_f32_e32 v122, v127, v127
	v_mul_f32_e32 v123, v129, v129
	v_fmac_f32_e32 v122, v126, v126
	v_fmac_f32_e32 v123, v128, v128
	v_add_f32_e32 v122, v122, v123
	v_mul_f32_e32 v123, v153, v153
	v_mul_f32_e32 v124, v151, v151
	v_fmac_f32_e32 v123, v152, v152
	v_fmac_f32_e32 v124, v150, v150
	v_add_f32_e32 v123, v123, v124
	v_add_f32_e32 v150, v122, v123
	v_mov_b32_e32 v122, v116
	v_mov_b32_e32 v123, v117
	v_mov_b32_e32 v124, v114
	v_mov_b32_e32 v125, v115
	v_cvt_pk_bf16_f32 v114, v118, v119
	v_cvt_pk_bf16_f32 v115, v120, v121
	v_cvt_pk_bf16_f32 v116, v124, v125
	v_cvt_pk_bf16_f32 v117, v122, v123
	global_store_dwordx4 v[154:155], v[114:117], off offset:256
	s_nop 1
	v_mul_f32_e32 v114, v119, v119
	v_mul_f32_e32 v115, v121, v121
	v_fmac_f32_e32 v114, v118, v118
	v_fmac_f32_e32 v115, v120, v120
	v_add_f32_e32 v114, v114, v115
	v_mul_f32_e32 v115, v125, v125
	v_mul_f32_e32 v116, v123, v123
	v_fmac_f32_e32 v115, v124, v124
	v_fmac_f32_e32 v116, v122, v122
	v_add_f32_e32 v115, v115, v116
	v_and_b32_e32 v116, 64, v191
	v_add_f32_e32 v114, v114, v115
	v_xor_b32_e32 v115, 16, v191
	v_add_u32_e32 v117, 64, v116
	v_cmp_lt_i32_e32 vcc, v115, v117
	v_add_f32_e32 v114, v150, v114
	s_nop 0
	v_cndmask_b32_e32 v115, v191, v115, vcc
	v_lshlrev_b32_e32 v116, 2, v115
	ds_bpermute_b32 v115, v116, v114
	s_waitcnt lgkmcnt(0)
	v_add_f32_e32 v114, v114, v115
	v_xor_b32_e32 v115, 32, v191
	v_cmp_lt_i32_e32 vcc, v115, v117
	s_nop 1
	v_cndmask_b32_e32 v115, v191, v115, vcc
	v_lshlrev_b32_e32 v117, 2, v115
	ds_bpermute_b32 v115, v117, v114
	s_and_saveexec_b64 s[2:3], s[0:1]
	s_cbranch_execz .LBB0_833
	v_readlane_b32 s20, v253, 11
	v_readlane_b32 s21, v253, 12
	s_waitcnt lgkmcnt(0)
	v_add_f32_e32 v114, v114, v115
	v_lshl_add_u64 v[118:119], v[168:169], 2, s[20:21]
	global_atomic_add_f32 v[118:119], v114, off
.LBB0_833:
	s_or_b64 exec, exec, s[2:3]
	v_or_b32_e32 v114, 16, v168
	s_waitcnt lgkmcnt(0)
	v_ashrrev_i32_e32 v115, 31, v114
	v_lshlrev_b64 v[118:119], 10, v[114:115]
	v_lshl_add_u64 v[118:119], v[118:119], 0, v[166:167]
	v_lshl_add_u64 v[122:123], v[118:119], 1, s[54:55]
	v_mov_b32_e32 v118, v108
	v_mov_b32_e32 v119, v109
	v_mov_b32_e32 v120, v106
	v_mov_b32_e32 v121, v107
	v_cvt_pk_bf16_f32 v106, v110, v111
	v_cvt_pk_bf16_f32 v107, v112, v113
	v_cvt_pk_bf16_f32 v108, v120, v121
	v_cvt_pk_bf16_f32 v109, v118, v119
	global_store_dwordx4 v[122:123], v[106:109], off
	s_nop 1
	v_mul_f32_e32 v106, v111, v111
	v_mul_f32_e32 v107, v113, v113
	v_fmac_f32_e32 v106, v110, v110
	v_fmac_f32_e32 v107, v112, v112
	v_add_f32_e32 v106, v106, v107
	v_mul_f32_e32 v107, v121, v121
	v_mul_f32_e32 v108, v119, v119
	v_fmac_f32_e32 v107, v120, v120
	v_fmac_f32_e32 v108, v118, v118
	v_add_f32_e32 v107, v107, v108
	v_add_f32_e32 v118, v106, v107
	v_mov_b32_e32 v106, v100
	v_mov_b32_e32 v107, v101
	v_mov_b32_e32 v108, v98
	v_mov_b32_e32 v109, v99
	v_cvt_pk_bf16_f32 v98, v102, v103
	v_cvt_pk_bf16_f32 v99, v104, v105
	v_cvt_pk_bf16_f32 v100, v108, v109
	v_cvt_pk_bf16_f32 v101, v106, v107
	global_store_dwordx4 v[122:123], v[98:101], off offset:256
	s_nop 1
	v_mul_f32_e32 v98, v103, v103
	v_mul_f32_e32 v99, v105, v105
	v_fmac_f32_e32 v98, v102, v102
	v_fmac_f32_e32 v99, v104, v104
	v_add_f32_e32 v98, v98, v99
	v_mul_f32_e32 v99, v109, v109
	v_mul_f32_e32 v100, v107, v107
	v_fmac_f32_e32 v99, v108, v108
	v_fmac_f32_e32 v100, v106, v106
	v_add_f32_e32 v99, v99, v100
	v_add_f32_e32 v98, v98, v99
	v_add_f32_e32 v98, v118, v98
	ds_bpermute_b32 v99, v116, v98
	s_waitcnt lgkmcnt(0)
	v_add_f32_e32 v98, v98, v99
	ds_bpermute_b32 v99, v117, v98
	s_and_saveexec_b64 s[2:3], s[0:1]
	s_cbranch_execz .LBB0_835
	v_readlane_b32 s20, v253, 11
	v_readlane_b32 s21, v253, 12
	s_waitcnt lgkmcnt(0)
	v_add_f32_e32 v98, v98, v99
	v_lshl_add_u64 v[100:101], v[114:115], 2, s[20:21]
	global_atomic_add_f32 v[100:101], v98, off
.LBB0_835:
	s_or_b64 exec, exec, s[2:3]
	v_or_b32_e32 v98, 32, v168
	s_waitcnt lgkmcnt(0)
	v_ashrrev_i32_e32 v99, 31, v98
	v_lshlrev_b64 v[100:101], 10, v[98:99]
	v_lshl_add_u64 v[100:101], v[100:101], 0, v[166:167]
	v_lshl_add_u64 v[104:105], v[100:101], 1, s[54:55]
	v_mov_b32_e32 v100, v92
	v_mov_b32_e32 v101, v93
	v_mov_b32_e32 v102, v90
	v_mov_b32_e32 v103, v91
	v_cvt_pk_bf16_f32 v90, v94, v95
	v_cvt_pk_bf16_f32 v91, v96, v97
	v_cvt_pk_bf16_f32 v92, v102, v103
	v_cvt_pk_bf16_f32 v93, v100, v101
	global_store_dwordx4 v[104:105], v[90:93], off
	s_nop 1
	v_mul_f32_e32 v90, v95, v95
	v_mul_f32_e32 v91, v97, v97
	v_fmac_f32_e32 v90, v94, v94
	v_fmac_f32_e32 v91, v96, v96
	v_add_f32_e32 v90, v90, v91
	v_mul_f32_e32 v91, v103, v103
	v_mul_f32_e32 v92, v101, v101
	v_fmac_f32_e32 v91, v102, v102
	v_fmac_f32_e32 v92, v100, v100
	v_add_f32_e32 v91, v91, v92
	v_add_f32_e32 v100, v90, v91
	v_mov_b32_e32 v90, v84
	v_mov_b32_e32 v91, v85
	v_mov_b32_e32 v92, v82
	v_mov_b32_e32 v93, v83
	v_cvt_pk_bf16_f32 v82, v86, v87
	v_cvt_pk_bf16_f32 v83, v88, v89
	v_cvt_pk_bf16_f32 v84, v92, v93
	v_cvt_pk_bf16_f32 v85, v90, v91
	global_store_dwordx4 v[104:105], v[82:85], off offset:256
	s_nop 1
	v_mul_f32_e32 v82, v87, v87
	v_mul_f32_e32 v83, v89, v89
	v_fmac_f32_e32 v82, v86, v86
	v_fmac_f32_e32 v83, v88, v88
	v_add_f32_e32 v82, v82, v83
	v_mul_f32_e32 v83, v93, v93
	v_mul_f32_e32 v84, v91, v91
	v_fmac_f32_e32 v83, v92, v92
	v_fmac_f32_e32 v84, v90, v90
	v_add_f32_e32 v83, v83, v84
	v_add_f32_e32 v82, v82, v83
	v_add_f32_e32 v82, v100, v82
	ds_bpermute_b32 v83, v116, v82
	s_waitcnt lgkmcnt(0)
	v_add_f32_e32 v82, v82, v83
	ds_bpermute_b32 v83, v117, v82
	s_and_saveexec_b64 s[2:3], s[0:1]
	s_cbranch_execz .LBB0_837
	v_readlane_b32 s20, v253, 11
	v_readlane_b32 s21, v253, 12
	s_waitcnt lgkmcnt(0)
	v_add_f32_e32 v82, v82, v83
	v_lshl_add_u64 v[84:85], v[98:99], 2, s[20:21]
	global_atomic_add_f32 v[84:85], v82, off
; __device__ __forceinline__ float bflo(unsigned u) { return __uint_as_float(u << 16); }
; __device__ __forceinline__ float bfhi(unsigned u) { return __uint_as_float(u & 0xffff0000u); }
; __device__ __forceinline__ unsigned pk2(float lo, float hi) { f32x2_t v = {lo, hi}; bf16x2_t b = __builtin_convertvector(v, bf16x2_t); return __builtin_bit_cast(unsigned, b); }
; __device__ __forceinline__ void atomic_add_agent(float* p, float v) { (void)__hip_atomic_fetch_add(p, v, __ATOMIC_RELAXED, __HIP_MEMORY_SCOPE_AGENT); }
;     __device__ __forceinline__ void operator()(const f32x4 (&acc)[2][2][4][2], const pg8::Unit& u, int wr, int wc, int fr, int fq) const {
;     ...
;                 const int row = row0 + ai * 128 + m * 16; float s2 = 0.f;
; #pragma unroll
;                 for (int bj = 0; bj < 2; ++bj) {
;                     const size_t off = (size_t)row * 1024 + c0 + bj * 128;
;                     f32x4 x0, x1;
;                     if (xin) { x0 = *(const f32x4*)(xin + off); x1 = *(const f32x4*)(xin + off + 4); }
;                     else { const v4u xv = *(const v4u*)(xb + off); x0 = (f32x4){bflo(xv.x), bfhi(xv.x), bflo(xv.y), bfhi(xv.y)}; x1 = (f32x4){bflo(xv.z), bfhi(xv.z), bflo(xv.w), bfhi(xv.w)}; }
;                     const f32x4 n0 = x0 + acc[ai][bj][m][0], n1 = x1 + acc[ai][bj][m][1];
;                     if (xout) { *(f32x4*)(xout + off) = n0; *(f32x4*)(xout + off + 4) = n1; }
;                     else *(v4u*)(xb + off) = (v4u){pk2(n0[0], n0[1]), pk2(n0[2], n0[3]), pk2(n1[0], n1[1]), pk2(n1[2], n1[3])};
;                     s2 += ((n0[0] * n0[0] + n0[1] * n0[1]) + (n0[2] * n0[2] + n0[3] * n0[3])) + ((n1[0] * n1[0] + n1[1] * n1[1]) + (n1[2] * n1[2] + n1[3] * n1[3]));
;                 }
;                 if (ssq) { s2 += __shfl_xor(s2, 16); s2 += __shfl_xor(s2, 32); if (fq == 0) atomic_add_agent(ssq + row, s2); }
.LBB0_837:
	s_or_b64 exec, exec, s[2:3]
	v_or_b32_e32 v82, 48, v168
	s_waitcnt lgkmcnt(0)
	v_ashrrev_i32_e32 v83, 31, v82
	v_lshlrev_b64 v[84:85], 10, v[82:83]
	v_lshl_add_u64 v[84:85], v[84:85], 0, v[166:167]
	v_lshl_add_u64 v[88:89], v[84:85], 1, s[54:55]
	v_mov_b32_e32 v84, v76
	v_mov_b32_e32 v85, v77
	v_mov_b32_e32 v86, v74
	v_mov_b32_e32 v87, v75
	v_cvt_pk_bf16_f32 v74, v78, v79
	v_cvt_pk_bf16_f32 v75, v80, v81
	v_cvt_pk_bf16_f32 v76, v86, v87
	v_cvt_pk_bf16_f32 v77, v84, v85
	global_store_dwordx4 v[88:89], v[74:77], off
	s_nop 1
	v_mul_f32_e32 v74, v79, v79
	v_mul_f32_e32 v75, v81, v81
	v_fmac_f32_e32 v74, v78, v78
	v_fmac_f32_e32 v75, v80, v80
	v_add_f32_e32 v74, v74, v75
	v_mul_f32_e32 v75, v87, v87
	v_mul_f32_e32 v76, v85, v85
	v_fmac_f32_e32 v75, v86, v86
	v_fmac_f32_e32 v76, v84, v84
	v_add_f32_e32 v75, v75, v76
	v_add_f32_e32 v84, v74, v75
	v_mov_b32_e32 v74, v68
	v_mov_b32_e32 v75, v69
	v_mov_b32_e32 v76, v66
	v_mov_b32_e32 v77, v67
	v_cvt_pk_bf16_f32 v66, v70, v71
	v_cvt_pk_bf16_f32 v67, v72, v73
	v_cvt_pk_bf16_f32 v68, v76, v77
	v_cvt_pk_bf16_f32 v69, v74, v75
	global_store_dwordx4 v[88:89], v[66:69], off offset:256
	s_nop 1
	v_mul_f32_e32 v66, v71, v71
	v_mul_f32_e32 v67, v73, v73
	v_fmac_f32_e32 v66, v70, v70
	v_fmac_f32_e32 v67, v72, v72
	v_add_f32_e32 v66, v66, v67
	v_mul_f32_e32 v67, v77, v77
	v_mul_f32_e32 v68, v75, v75
	v_fmac_f32_e32 v67, v76, v76
	v_fmac_f32_e32 v68, v74, v74
	v_add_f32_e32 v67, v67, v68
	v_add_f32_e32 v66, v66, v67
	v_add_f32_e32 v66, v84, v66
	ds_bpermute_b32 v67, v116, v66
	s_waitcnt lgkmcnt(0)
	v_add_f32_e32 v66, v66, v67
	ds_bpermute_b32 v67, v117, v66
	s_and_saveexec_b64 s[2:3], s[0:1]
	s_cbranch_execz .LBB0_839
	v_readlane_b32 s20, v253, 11
	v_readlane_b32 s21, v253, 12
	s_waitcnt lgkmcnt(0)
	v_add_f32_e32 v66, v66, v67
	v_lshl_add_u64 v[68:69], v[82:83], 2, s[20:21]
	global_atomic_add_f32 v[68:69], v66, off
.LBB0_839:
	s_or_b64 exec, exec, s[2:3]
	v_add_u32_e32 v66, 0x80, v168
	s_waitcnt lgkmcnt(0)
	v_ashrrev_i32_e32 v67, 31, v66
	v_lshlrev_b64 v[68:69], 10, v[66:67]
	v_lshl_add_u64 v[68:69], v[68:69], 0, v[166:167]
	v_lshl_add_u64 v[72:73], v[68:69], 1, s[54:55]
	v_mov_b32_e32 v68, v60
	v_mov_b32_e32 v69, v61
	v_mov_b32_e32 v70, v58
	v_mov_b32_e32 v71, v59
	v_cvt_pk_bf16_f32 v58, v62, v63
	v_cvt_pk_bf16_f32 v59, v64, v65
	v_cvt_pk_bf16_f32 v60, v70, v71
	v_cvt_pk_bf16_f32 v61, v68, v69
	global_store_dwordx4 v[72:73], v[58:61], off
	s_nop 1
	v_mul_f32_e32 v58, v63, v63
	v_mul_f32_e32 v59, v65, v65
	v_fmac_f32_e32 v58, v62, v62
	v_fmac_f32_e32 v59, v64, v64
	v_add_f32_e32 v58, v58, v59
	v_mul_f32_e32 v59, v71, v71
	v_mul_f32_e32 v60, v69, v69
	v_fmac_f32_e32 v59, v70, v70
	v_fmac_f32_e32 v60, v68, v68
	v_add_f32_e32 v59, v59, v60
	v_add_f32_e32 v68, v58, v59
	v_mov_b32_e32 v58, v52
	v_mov_b32_e32 v59, v53
	v_mov_b32_e32 v60, v50
	v_mov_b32_e32 v61, v51
	v_cvt_pk_bf16_f32 v50, v54, v55
	v_cvt_pk_bf16_f32 v51, v56, v57
	v_cvt_pk_bf16_f32 v52, v60, v61
	v_cvt_pk_bf16_f32 v53, v58, v59
	global_store_dwordx4 v[72:73], v[50:53], off offset:256
	s_nop 1
	v_mul_f32_e32 v50, v55, v55
	v_mul_f32_e32 v51, v57, v57
	v_fmac_f32_e32 v50, v54, v54
	v_fmac_f32_e32 v51, v56, v56
	v_add_f32_e32 v50, v50, v51
	v_mul_f32_e32 v51, v61, v61
	v_mul_f32_e32 v52, v59, v59
	v_fmac_f32_e32 v51, v60, v60
	v_fmac_f32_e32 v52, v58, v58
	v_add_f32_e32 v51, v51, v52
	v_add_f32_e32 v50, v50, v51
	v_add_f32_e32 v50, v68, v50
	ds_bpermute_b32 v51, v116, v50
	s_waitcnt lgkmcnt(0)
	v_add_f32_e32 v50, v50, v51
	ds_bpermute_b32 v51, v117, v50
	s_and_saveexec_b64 s[2:3], s[0:1]
	s_cbranch_execz .LBB0_841
	v_readlane_b32 s20, v253, 11
	v_readlane_b32 s21, v253, 12
	s_waitcnt lgkmcnt(0)
	v_add_f32_e32 v50, v50, v51
	v_lshl_add_u64 v[52:53], v[66:67], 2, s[20:21]
	global_atomic_add_f32 v[52:53], v50, off
; __device__ __forceinline__ float bflo(unsigned u) { return __uint_as_float(u << 16); }
; __device__ __forceinline__ float bfhi(unsigned u) { return __uint_as_float(u & 0xffff0000u); }
; __device__ __forceinline__ unsigned pk2(float lo, float hi) { f32x2_t v = {lo, hi}; bf16x2_t b = __builtin_convertvector(v, bf16x2_t); return __builtin_bit_cast(unsigned, b); }
; __device__ __forceinline__ void atomic_add_agent(float* p, float v) { (void)__hip_atomic_fetch_add(p, v, __ATOMIC_RELAXED, __HIP_MEMORY_SCOPE_AGENT); }
;     __device__ __forceinline__ void operator()(const f32x4 (&acc)[2][2][4][2], const pg8::Unit& u, int wr, int wc, int fr, int fq) const {
;     ...
;                 const int row = row0 + ai * 128 + m * 16; float s2 = 0.f;
; #pragma unroll
;                 for (int bj = 0; bj < 2; ++bj) {
;                     const size_t off = (size_t)row * 1024 + c0 + bj * 128;
;                     f32x4 x0, x1;
;                     if (xin) { x0 = *(const f32x4*)(xin + off); x1 = *(const f32x4*)(xin + off + 4); }
;                     else { const v4u xv = *(const v4u*)(xb + off); x0 = (f32x4){bflo(xv.x), bfhi(xv.x), bflo(xv.y), bfhi(xv.y)}; x1 = (f32x4){bflo(xv.z), bfhi(xv.z), bflo(xv.w), bfhi(xv.w)}; }
;                     const f32x4 n0 = x0 + acc[ai][bj][m][0], n1 = x1 + acc[ai][bj][m][1];
;                     if (xout) { *(f32x4*)(xout + off) = n0; *(f32x4*)(xout + off + 4) = n1; }
;                     else *(v4u*)(xb + off) = (v4u){pk2(n0[0], n0[1]), pk2(n0[2], n0[3]), pk2(n1[0], n1[1]), pk2(n1[2], n1[3])};
;                     s2 += ((n0[0] * n0[0] + n0[1] * n0[1]) + (n0[2] * n0[2] + n0[3] * n0[3])) + ((n1[0] * n1[0] + n1[1] * n1[1]) + (n1[2] * n1[2] + n1[3] * n1[3]));
;                 }
;                 if (ssq) { s2 += __shfl_xor(s2, 16); s2 += __shfl_xor(s2, 32); if (fq == 0) atomic_add_agent(ssq + row, s2); }
.LBB0_841:
	s_or_b64 exec, exec, s[2:3]
	v_add_u32_e32 v50, 0x90, v168
	s_waitcnt lgkmcnt(0)
	v_ashrrev_i32_e32 v51, 31, v50
	v_lshlrev_b64 v[52:53], 10, v[50:51]
	v_lshl_add_u64 v[52:53], v[52:53], 0, v[166:167]
	v_lshl_add_u64 v[56:57], v[52:53], 1, s[54:55]
	v_mov_b32_e32 v52, v44
	v_mov_b32_e32 v53, v45
	v_mov_b32_e32 v54, v42
	v_mov_b32_e32 v55, v43
	v_cvt_pk_bf16_f32 v42, v46, v47
	v_cvt_pk_bf16_f32 v43, v48, v49
	v_cvt_pk_bf16_f32 v44, v54, v55
	v_cvt_pk_bf16_f32 v45, v52, v53
	global_store_dwordx4 v[56:57], v[42:45], off
	s_nop 1
	v_mul_f32_e32 v42, v47, v47
	v_mul_f32_e32 v43, v49, v49
	v_fmac_f32_e32 v42, v46, v46
	v_fmac_f32_e32 v43, v48, v48
	v_add_f32_e32 v42, v42, v43
	v_mul_f32_e32 v43, v55, v55
	v_mul_f32_e32 v44, v53, v53
	v_fmac_f32_e32 v43, v54, v54
	v_fmac_f32_e32 v44, v52, v52
	v_add_f32_e32 v43, v43, v44
	v_add_f32_e32 v52, v42, v43
	v_mov_b32_e32 v42, v36
	v_mov_b32_e32 v43, v37
	v_mov_b32_e32 v44, v34
	v_mov_b32_e32 v45, v35
	v_cvt_pk_bf16_f32 v34, v38, v39
	v_cvt_pk_bf16_f32 v35, v40, v41
	v_cvt_pk_bf16_f32 v36, v44, v45
	v_cvt_pk_bf16_f32 v37, v42, v43
	global_store_dwordx4 v[56:57], v[34:37], off offset:256
	s_nop 1
	v_mul_f32_e32 v34, v39, v39
	v_mul_f32_e32 v35, v41, v41
	v_fmac_f32_e32 v34, v38, v38
	v_fmac_f32_e32 v35, v40, v40
	v_add_f32_e32 v34, v34, v35
	v_mul_f32_e32 v35, v45, v45
	v_mul_f32_e32 v36, v43, v43
	v_fmac_f32_e32 v35, v44, v44
	v_fmac_f32_e32 v36, v42, v42
	v_add_f32_e32 v35, v35, v36
	v_add_f32_e32 v34, v34, v35
	v_add_f32_e32 v34, v52, v34
	ds_bpermute_b32 v35, v116, v34
	s_waitcnt lgkmcnt(0)
	v_add_f32_e32 v34, v34, v35
	ds_bpermute_b32 v35, v117, v34
	s_and_saveexec_b64 s[2:3], s[0:1]
	s_cbranch_execz .LBB0_843
	v_readlane_b32 s20, v253, 11
	v_readlane_b32 s21, v253, 12
	s_waitcnt lgkmcnt(0)
	v_add_f32_e32 v34, v34, v35
	v_lshl_add_u64 v[36:37], v[50:51], 2, s[20:21]
	global_atomic_add_f32 v[36:37], v34, off
.LBB0_843:
	s_or_b64 exec, exec, s[2:3]
	v_add_u32_e32 v34, 0xa0, v168
	s_waitcnt lgkmcnt(0)
	v_ashrrev_i32_e32 v35, 31, v34
	v_lshlrev_b64 v[36:37], 10, v[34:35]
	v_lshl_add_u64 v[36:37], v[36:37], 0, v[166:167]
	v_lshl_add_u64 v[40:41], v[36:37], 1, s[54:55]
	v_mov_b32_e32 v36, v28
	v_mov_b32_e32 v37, v29
	v_mov_b32_e32 v38, v26
	v_mov_b32_e32 v39, v27
	v_cvt_pk_bf16_f32 v26, v30, v31
	v_cvt_pk_bf16_f32 v27, v32, v33
	v_cvt_pk_bf16_f32 v28, v38, v39
	v_cvt_pk_bf16_f32 v29, v36, v37
	global_store_dwordx4 v[40:41], v[26:29], off
	s_nop 1
	v_mul_f32_e32 v26, v31, v31
	v_mul_f32_e32 v27, v33, v33
	v_fmac_f32_e32 v26, v30, v30
	v_fmac_f32_e32 v27, v32, v32
	v_add_f32_e32 v26, v26, v27
	v_mul_f32_e32 v27, v39, v39
	v_mul_f32_e32 v28, v37, v37
	v_fmac_f32_e32 v27, v38, v38
	v_fmac_f32_e32 v28, v36, v36
	v_add_f32_e32 v27, v27, v28
	v_add_f32_e32 v36, v26, v27
	v_mov_b32_e32 v26, v20
	v_mov_b32_e32 v27, v21
	v_mov_b32_e32 v28, v18
	v_mov_b32_e32 v29, v19
	v_cvt_pk_bf16_f32 v18, v22, v23
	v_cvt_pk_bf16_f32 v19, v24, v25
	v_cvt_pk_bf16_f32 v20, v28, v29
	v_cvt_pk_bf16_f32 v21, v26, v27
	global_store_dwordx4 v[40:41], v[18:21], off offset:256
	s_nop 1
	v_mul_f32_e32 v18, v23, v23
	v_mul_f32_e32 v19, v25, v25
	v_fmac_f32_e32 v18, v22, v22
	v_fmac_f32_e32 v19, v24, v24
	v_add_f32_e32 v18, v18, v19
	v_mul_f32_e32 v19, v29, v29
	v_mul_f32_e32 v20, v27, v27
	v_fmac_f32_e32 v19, v28, v28
	v_fmac_f32_e32 v20, v26, v26
	v_add_f32_e32 v19, v19, v20
	v_add_f32_e32 v18, v18, v19
	v_add_f32_e32 v18, v36, v18
	ds_bpermute_b32 v19, v116, v18
	s_waitcnt lgkmcnt(0)
	v_add_f32_e32 v18, v18, v19
	ds_bpermute_b32 v19, v117, v18
	s_and_saveexec_b64 s[2:3], s[0:1]
	s_cbranch_execz .LBB0_845
	v_readlane_b32 s20, v253, 11
	v_readlane_b32 s21, v253, 12
	s_waitcnt lgkmcnt(0)
	v_add_f32_e32 v18, v18, v19
	v_lshl_add_u64 v[20:21], v[34:35], 2, s[20:21]
	global_atomic_add_f32 v[20:21], v18, off
.LBB0_845:
	s_or_b64 exec, exec, s[2:3]
	v_add_u32_e32 v18, 0xb0, v168
	s_waitcnt lgkmcnt(0)
	v_ashrrev_i32_e32 v19, 31, v18
	v_lshlrev_b64 v[20:21], 10, v[18:19]
	v_lshl_add_u64 v[20:21], v[20:21], 0, v[166:167]
	v_lshl_add_u64 v[24:25], v[20:21], 1, s[54:55]
	v_mov_b32_e32 v20, v12
	v_mov_b32_e32 v21, v13
	v_mov_b32_e32 v22, v10
	v_mov_b32_e32 v23, v11
	v_cvt_pk_bf16_f32 v10, v14, v15
	v_cvt_pk_bf16_f32 v11, v16, v17
	v_cvt_pk_bf16_f32 v12, v22, v23
	v_cvt_pk_bf16_f32 v13, v20, v21
	global_store_dwordx4 v[24:25], v[10:13], off
	s_nop 1
	v_mul_f32_e32 v10, v15, v15
	v_mul_f32_e32 v11, v17, v17
	v_fmac_f32_e32 v10, v14, v14
	v_fmac_f32_e32 v11, v16, v16
	v_add_f32_e32 v10, v10, v11
	v_mul_f32_e32 v11, v23, v23
	v_mul_f32_e32 v12, v21, v21
	v_fmac_f32_e32 v11, v22, v22
	v_fmac_f32_e32 v12, v20, v20
	v_add_f32_e32 v11, v11, v12
	v_add_f32_e32 v20, v10, v11
	v_mov_b32_e32 v10, v4
	v_mov_b32_e32 v11, v5
	v_mov_b32_e32 v12, v2
	v_mov_b32_e32 v13, v3
	v_cvt_pk_bf16_f32 v2, v6, v7
	v_cvt_pk_bf16_f32 v3, v8, v9
	v_cvt_pk_bf16_f32 v4, v12, v13
	v_cvt_pk_bf16_f32 v5, v10, v11
	global_store_dwordx4 v[24:25], v[2:5], off offset:256
	s_nop 1
	v_mul_f32_e32 v2, v7, v7
	v_mul_f32_e32 v3, v9, v9
	v_fmac_f32_e32 v2, v6, v6
	v_fmac_f32_e32 v3, v8, v8
	v_add_f32_e32 v2, v2, v3
	v_mul_f32_e32 v3, v13, v13
	v_mul_f32_e32 v4, v11, v11
	v_fmac_f32_e32 v3, v12, v12
	v_fmac_f32_e32 v4, v10, v10
	v_add_f32_e32 v3, v3, v4
	v_add_f32_e32 v2, v2, v3
	v_add_f32_e32 v2, v20, v2
	ds_bpermute_b32 v3, v116, v2
	s_waitcnt lgkmcnt(0)
	v_add_f32_e32 v2, v2, v3
	ds_bpermute_b32 v3, v117, v2
	s_and_saveexec_b64 s[2:3], s[0:1]
	s_cbranch_execz .LBB0_847
	v_readlane_b32 s20, v253, 11
	v_readlane_b32 s21, v253, 12
	s_waitcnt lgkmcnt(0)
	v_add_f32_e32 v2, v2, v3
	v_lshl_add_u64 v[4:5], v[18:19], 2, s[20:21]
	global_atomic_add_f32 v[4:5], v2, off
